# adds: in rotation-free 16-MFMA groups the two k-steps of each accumulator are issued back to back (31 groups)
# speedup vs baseline: 1.0143x; 1.0143x over previous
;     __host__ __device__ __forceinline__ bool next(int i, Unit& u) const { const int vv = vid + (i / 5) * G; if (vv >= 256) return false; u.pm = vv >> 2; u.pn = (vv & 3) + 4 * (i % 5); return true; }
; #define PG8_STAGE(bufoff, gbase, voff) do { _Pragma("unroll") for (int _i = 0; _i < 2; ++_i) \
;         __builtin_amdgcn_global_load_lds((const unsigned*)((const char*)(gbase) + (voff)[_i]), (PG8_LAS unsigned*)(lds + (bufoff) + ldsw + _i * 8192), 16, 0, 0); } while (0)
; #define PG8_LDA(dst, b, h) do { _Pragma("unroll") for (int m = 0; m < 4; ++m) _Pragma("unroll") for (int k = 0; k < 2; ++k) dst[m][k] = *(const PG8_LAS bf16x8*)(lds + PG8_SA(b, h) + aoff + m * 2048 + k * 1024); } while (0)
; #define PG8_LDB(dst, b, h) do { _Pragma("unroll") for (int n = 0; n < 2; ++n) _Pragma("unroll") for (int k = 0; k < 2; ++k) dst[n][k] = *(const PG8_LAS bf16x8*)(lds + PG8_SB(b, h) + boff + n * 2048 + k * 1024); } while (0)
; #define PG8_WAIT_V(n) asm volatile("s_waitcnt vmcnt(" #n ")" ::: "memory")
; #define PG8_WAIT_L(n) asm volatile("s_waitcnt lgkmcnt(" #n ")" ::: "memory")
; #define PG8_BAR __builtin_amdgcn_s_barrier()
;     ...
;         const bool has_next = S.next(ui + 1, nxt);
;         const char* nA = has_next ? (const char*)g.A + (size_t)nxt.pm * tstepA + (size_t)nxt.pn * APN + kofA : cA; const char* nB = has_next ? (const char*)g.Bt + (size_t)nxt.pn * tstepB + S.b_off(nxt) + kofB : cB;
;         for (int t = 0; t < nt; t += 2) {
;             const bool last = (t == nt - 2);
;             const char* a1 = cA + (ptrdiff_t)(t + 1) * kstepA;
;             const char* a2 = last ? nA : cA + (ptrdiff_t)(t + 2) * kstepA; const char* b2 = last ? nB : cB + (ptrdiff_t)(t + 2) * kstep;
;             const char* a3 = a2 + kstepA; const char* b3 = b2 + kstep;
;             if (last && has_next) S.a_ready(nxt);
;             if constexpr (SP2) {
;             PG8_LDB(B0, 0, 0); PG8_LDB(B1, 0, 1); PG8_SCHED; PG8_LDA(At, 0, 0); PG8_STAGE(PG8_SA(1, 1), a1 + hstepA, voffA);
;             PG8_WAIT_V(8); PG8_WAIT_L(0); PG8_BAR; PG8_MMA(0, 0, At, B0); PG8_MMA(0, 1, At, B1); PG8_BAR; PG8_SCHED;
;             PG8_LDA(At, 0, 1); PG8_STAGE(PG8_SB(0, 0), b2, voffB); PG8_STAGE(PG8_SB(0, 1), b2 + hstepB, voffB); PG8_STAGE(PG8_SA(0, 0), a2, voffA);
;     __device__ __forceinline__ size_t b_off(const pg8::Unit& u) const { return (size_t)(u.pm >> 3) * 4 * 131072; }
.LBB0_97:
	s_mov_b64 s[30:31], s[6:7]
	s_ashr_i32 s6, s14, 2
	s_and_b32 s6, s6, -8
	s_and_b32 s7, s14, 7
	s_mov_b32 s20, s58
	s_mov_b32 s21, s57
	v_cmp_lt_i64_e64 s[4:5], s[14:15], v[138:139]
	s_bfe_u32 s57, s14, 0x20003
	s_or_b32 s58, s6, s7
	s_and_b64 s[6:7], s[4:5], exec
	s_cselect_b32 s24, s58, s20
	s_cselect_b32 s6, s57, s21
	s_ashr_i32 s25, s24, 31
	s_lshl_b64 s[20:21], s[24:25], 20
	s_add_u32 s20, s2, s20
	s_addc_u32 s21, s3, s21
	s_ashr_i32 s7, s6, 31
	s_lshl_b64 s[6:7], s[6:7], 17
	s_add_u32 s20, s20, s6
	s_addc_u32 s21, s21, s7
	s_and_b64 s[28:29], s[4:5], exec
	ds_read_b128 v[0:3], v141
	ds_read_b128 v[4:7], v141 offset:1024
	ds_read_b128 v[8:11], v141 offset:2048
	ds_read_b128 v[12:15], v141 offset:3072
	ds_read_b128 v[16:19], v142
	ds_read_b128 v[20:23], v142 offset:1024
	ds_read_b128 v[24:27], v142 offset:2048
	ds_read_b128 v[28:31], v142 offset:3072
	s_cselect_b32 s29, s21, s27
	s_cselect_b32 s28, s20, s26
	s_add_u32 s25, s33, s6
	s_addc_u32 s34, s36, s7
	s_ashr_i32 s6, s24, 3
	s_ashr_i32 s7, s6, 31
	s_lshl_b64 s[6:7], s[6:7], 19
	s_add_u32 s6, s25, s6
	s_addc_u32 s7, s34, s7
	s_and_b64 s[24:25], s[4:5], exec
	s_cselect_b32 s25, s7, s31
	s_cselect_b32 s24, s6, s30
	s_add_u32 s60, s26, 0x10000
	s_addc_u32 s61, s27, 0
	s_add_u32 s34, s26, 0x18000
	s_addc_u32 s35, s27, 0
	s_add_u32 s62, s26, 0xc000
	s_addc_u32 s63, s27, 0
	s_mov_b32 m0, s46
	ds_read_b128 v[32:35], v143
	ds_read_b128 v[36:39], v143 offset:1024
	ds_read_b128 v[40:43], v143 offset:2048
	ds_read_b128 v[44:47], v143 offset:3072
	ds_read_b128 v[48:51], v143 offset:4096
	ds_read_b128 v[52:55], v143 offset:5120
	ds_read_b128 v[56:59], v143 offset:6144
	ds_read_b128 v[60:63], v143 offset:7168
	global_load_lds_dwordx4 v134, s[62:63]
	v_lshl_add_u64 v[64:65], s[62:63], 0, v[130:131]
	s_mov_b32 m0, s47
	s_nop 0
	global_load_lds_dwordx4 v[64:65], off
	s_waitcnt vmcnt(8)
	s_waitcnt lgkmcnt(0)
	s_barrier
	s_setprio 1
	s_waitcnt lgkmcnt(0)
	v_mfma_f32_16x16x32_bf16 v[64:67], v[0:3], v[32:35], 0
	v_mfma_f32_16x16x32_bf16 v[68:71], v[8:11], v[32:35], 0
	v_mfma_f32_16x16x32_bf16 v[72:75], v[0:3], v[40:43], 0
	v_mfma_f32_16x16x32_bf16 v[76:79], v[8:11], v[40:43], 0
	v_mfma_f32_16x16x32_bf16 v[80:83], v[0:3], v[48:51], 0
	v_mfma_f32_16x16x32_bf16 v[84:87], v[8:11], v[48:51], 0
	v_mfma_f32_16x16x32_bf16 v[88:91], v[0:3], v[56:59], 0
	v_mfma_f32_16x16x32_bf16 v[92:95], v[8:11], v[56:59], 0
	v_mfma_f32_16x16x32_bf16 v[64:67], v[4:7], v[36:39], v[64:67]
	v_mfma_f32_16x16x32_bf16 v[68:71], v[12:15], v[36:39], v[68:71]
	v_mfma_f32_16x16x32_bf16 v[72:75], v[4:7], v[44:47], v[72:75]
	v_mfma_f32_16x16x32_bf16 v[76:79], v[12:15], v[44:47], v[76:79]
	v_mfma_f32_16x16x32_bf16 v[80:83], v[4:7], v[52:55], v[80:83]
	v_mfma_f32_16x16x32_bf16 v[84:87], v[12:15], v[52:55], v[84:87]
	v_mfma_f32_16x16x32_bf16 v[88:91], v[4:7], v[60:63], v[88:91]
	v_mfma_f32_16x16x32_bf16 v[92:95], v[12:15], v[60:63], v[92:95]
	s_setprio 0
	s_setprio 1
	v_mfma_f32_16x16x32_bf16 v[96:99], v[16:19], v[32:35], 0
	v_mfma_f32_16x16x32_bf16 v[32:35], v[24:27], v[32:35], 0
	v_mfma_f32_16x16x32_bf16 v[96:99], v[20:23], v[36:39], v[96:99]
	v_mfma_f32_16x16x32_bf16 v[32:35], v[28:31], v[36:39], v[32:35]
	v_mfma_f32_16x16x32_bf16 v[36:39], v[16:19], v[40:43], 0
	v_mfma_f32_16x16x32_bf16 v[40:43], v[24:27], v[40:43], 0
	v_mfma_f32_16x16x32_bf16 v[36:39], v[20:23], v[44:47], v[36:39]
	v_mfma_f32_16x16x32_bf16 v[40:43], v[28:31], v[44:47], v[40:43]
	v_mfma_f32_16x16x32_bf16 v[44:47], v[16:19], v[48:51], 0
	v_mfma_f32_16x16x32_bf16 v[48:51], v[24:27], v[48:51], 0
	v_mfma_f32_16x16x32_bf16 v[44:47], v[20:23], v[52:55], v[44:47]
	v_mfma_f32_16x16x32_bf16 v[48:51], v[28:31], v[52:55], v[48:51]
	v_mfma_f32_16x16x32_bf16 v[52:55], v[16:19], v[56:59], 0
	v_mfma_f32_16x16x32_bf16 v[56:59], v[24:27], v[56:59], 0
	v_mfma_f32_16x16x32_bf16 v[52:55], v[20:23], v[60:63], v[52:55]
	v_mfma_f32_16x16x32_bf16 v[56:59], v[28:31], v[60:63], v[56:59]
	s_setprio 0
	s_barrier
	v_lshl_add_u64 v[210:211], s[30:31], 0, v[132:133]
	s_mov_b32 m0, s48
	v_lshl_add_u64 v[146:147], v[210:211], 0, s[16:17]
	v_lshl_add_u64 v[212:213], s[30:31], 0, v[128:129]
	s_add_u32 s62, s30, 0x10100
	ds_read_b128 v[60:63], v143 offset:16384
	ds_read_b128 v[100:103], v143 offset:17408
	ds_read_b128 v[104:107], v143 offset:18432
	ds_read_b128 v[108:111], v143 offset:19456
	ds_read_b128 v[112:115], v143 offset:20480
	ds_read_b128 v[116:119], v143 offset:21504
	ds_read_b128 v[120:123], v143 offset:22528
	ds_read_b128 v[124:127], v143 offset:23552
	global_load_lds_dwordx4 v[146:147], off
	v_lshl_add_u64 v[146:147], v[212:213], 0, s[16:17]
	s_mov_b32 m0, s50
	s_addc_u32 s63, s31, 0
	global_load_lds_dwordx4 v[146:147], off
	s_mov_b32 m0, s51
	s_nop 0
	global_load_lds_dwordx4 v132, s[62:63]
	s_mov_b32 m0, s52
	s_nop 0
	global_load_lds_dwordx4 v128, s[62:63]
	s_mov_b32 m0, s23
	s_nop 0
	global_load_lds_dwordx4 v134, s[60:61]
	v_lshl_add_u64 v[146:147], s[60:61], 0, v[130:131]
	s_mov_b32 m0, s37
	s_nop 0
	global_load_lds_dwordx4 v[146:147], off
	s_waitcnt vmcnt(8)
	s_waitcnt lgkmcnt(0)
	s_barrier
; #define PG8_STAGE(bufoff, gbase, voff) do { _Pragma("unroll") for (int _i = 0; _i < 2; ++_i) \
;         __builtin_amdgcn_global_load_lds((const unsigned*)((const char*)(gbase) + (voff)[_i]), (PG8_LAS unsigned*)(lds + (bufoff) + ldsw + _i * 8192), 16, 0, 0); } while (0)
; #define PG8_LDA(dst, b, h) do { _Pragma("unroll") for (int m = 0; m < 4; ++m) _Pragma("unroll") for (int k = 0; k < 2; ++k) dst[m][k] = *(const PG8_LAS bf16x8*)(lds + PG8_SA(b, h) + aoff + m * 2048 + k * 1024); } while (0)
; #define PG8_LDB(dst, b, h) do { _Pragma("unroll") for (int n = 0; n < 2; ++n) _Pragma("unroll") for (int k = 0; k < 2; ++k) dst[n][k] = *(const PG8_LAS bf16x8*)(lds + PG8_SB(b, h) + boff + n * 2048 + k * 1024); } while (0)
; #define PG8_MMA(ai, bj, At, Bt) do { __builtin_amdgcn_s_setprio(1); _Pragma("unroll") for (int m = 0; m < 4; ++m) _Pragma("unroll") for (int n = 0; n < 2; ++n) _Pragma("unroll") for (int k = 0; k < 2; ++k) \
;         acc[ai][bj][m][n] = __builtin_amdgcn_mfma_f32_16x16x32_bf16(Bt[n][k], At[m][k], acc[ai][bj][m][n], 0, 0, 0); __builtin_amdgcn_s_setprio(0); } while (0)
; #define PG8_WAIT_V(n) asm volatile("s_waitcnt vmcnt(" #n ")" ::: "memory")
; #define PG8_WAIT_L(n) asm volatile("s_waitcnt lgkmcnt(" #n ")" ::: "memory")
; #define PG8_BAR __builtin_amdgcn_s_barrier()
; #define PG8_SCHED __builtin_amdgcn_sched_barrier(0)
;     ...
;             PG8_LDA(At, 0, 1); PG8_STAGE(PG8_SB(0, 0), b2, voffB); PG8_STAGE(PG8_SB(0, 1), b2 + hstepB, voffB); PG8_STAGE(PG8_SA(0, 0), a2, voffA);
;             PG8_WAIT_V(8); PG8_WAIT_L(0); PG8_BAR; PG8_MMA(1, 0, At, B0); PG8_MMA(1, 1, At, B1); PG8_BAR; PG8_SCHED;
;             PG8_LDB(B0, 1, 0); PG8_LDB(B1, 1, 1); PG8_SCHED; PG8_LDA(At, 1, 0); PG8_STAGE(PG8_SA(0, 1), a2 + hstepA, voffA);
;             PG8_WAIT_V(8); PG8_WAIT_L(0); PG8_BAR; PG8_MMA(0, 0, At, B0); PG8_MMA(0, 1, At, B1); PG8_BAR; PG8_SCHED;
	s_setprio 1
	s_waitcnt lgkmcnt(0)
	v_mfma_f32_16x16x32_bf16 v[146:149], v[0:3], v[60:63], 0
	v_mfma_f32_16x16x32_bf16 v[154:157], v[0:3], v[104:107], 0
	v_mfma_f32_16x16x32_bf16 v[162:165], v[0:3], v[112:115], 0
	v_mfma_f32_16x16x32_bf16 v[0:3], v[0:3], v[120:123], 0
	v_mfma_f32_16x16x32_bf16 v[146:149], v[4:7], v[100:103], v[146:149]
	v_mfma_f32_16x16x32_bf16 v[154:157], v[4:7], v[108:111], v[154:157]
	v_mfma_f32_16x16x32_bf16 v[162:165], v[4:7], v[116:119], v[162:165]
	v_mfma_f32_16x16x32_bf16 v[0:3], v[4:7], v[124:127], v[0:3]
	v_mfma_f32_16x16x32_bf16 v[4:7], v[8:11], v[120:123], 0
	v_mfma_f32_16x16x32_bf16 v[150:153], v[8:11], v[60:63], 0
	v_mfma_f32_16x16x32_bf16 v[158:161], v[8:11], v[104:107], 0
	v_mfma_f32_16x16x32_bf16 v[166:169], v[8:11], v[112:115], 0
	v_mfma_f32_16x16x32_bf16 v[4:7], v[12:15], v[124:127], v[4:7]
	v_mfma_f32_16x16x32_bf16 v[150:153], v[12:15], v[100:103], v[150:153]
	v_mfma_f32_16x16x32_bf16 v[158:161], v[12:15], v[108:111], v[158:161]
	v_mfma_f32_16x16x32_bf16 v[166:169], v[12:15], v[116:119], v[166:169]
	s_setprio 0
	s_setprio 1
	v_mfma_f32_16x16x32_bf16 v[8:11], v[16:19], v[60:63], 0
	v_mfma_f32_16x16x32_bf16 v[12:15], v[24:27], v[60:63], 0
	v_mfma_f32_16x16x32_bf16 v[8:11], v[20:23], v[100:103], v[8:11]
	v_mfma_f32_16x16x32_bf16 v[12:15], v[28:31], v[100:103], v[12:15]
	v_mfma_f32_16x16x32_bf16 v[60:63], v[16:19], v[104:107], 0
	v_mfma_f32_16x16x32_bf16 v[100:103], v[24:27], v[104:107], 0
	v_mfma_f32_16x16x32_bf16 v[104:107], v[16:19], v[112:115], 0
	v_mfma_f32_16x16x32_bf16 v[16:19], v[16:19], v[120:123], 0
	v_mfma_f32_16x16x32_bf16 v[60:63], v[20:23], v[108:111], v[60:63]
	v_mfma_f32_16x16x32_bf16 v[100:103], v[28:31], v[108:111], v[100:103]
	v_mfma_f32_16x16x32_bf16 v[104:107], v[20:23], v[116:119], v[104:107]
	v_mfma_f32_16x16x32_bf16 v[108:111], v[24:27], v[112:115], 0
	v_mfma_f32_16x16x32_bf16 v[16:19], v[20:23], v[124:127], v[16:19]
	v_mfma_f32_16x16x32_bf16 v[20:23], v[24:27], v[120:123], 0
	v_mfma_f32_16x16x32_bf16 v[108:111], v[28:31], v[116:119], v[108:111]
	v_mfma_f32_16x16x32_bf16 v[20:23], v[28:31], v[124:127], v[20:23]
	s_setprio 0
	s_barrier
	ds_read_b128 v[24:27], v144
	ds_read_b128 v[28:31], v144 offset:1024
	ds_read_b128 v[112:115], v144 offset:2048
	ds_read_b128 v[116:119], v144 offset:3072
	ds_read_b128 v[120:123], v145
	ds_read_b128 v[124:127], v145 offset:1024
	ds_read_b128 v[170:173], v145 offset:2048
	ds_read_b128 v[174:177], v145 offset:3072
	s_add_u32 s60, s26, 0x14000
	s_addc_u32 s61, s27, 0
	s_mov_b32 m0, s39
	ds_read_b128 v[178:181], v143 offset:32768
	ds_read_b128 v[182:185], v143 offset:33792
	ds_read_b128 v[186:189], v143 offset:34816
	ds_read_b128 v[190:193], v143 offset:35840
	ds_read_b128 v[194:197], v143 offset:36864
	ds_read_b128 v[198:201], v143 offset:37888
	ds_read_b128 v[202:205], v143 offset:38912
	ds_read_b128 v[206:209], v143 offset:39936
	global_load_lds_dwordx4 v134, s[60:61]
	v_lshl_add_u64 v[214:215], s[60:61], 0, v[130:131]
	s_mov_b32 m0, s40
	s_nop 0
	global_load_lds_dwordx4 v[214:215], off
	s_waitcnt vmcnt(8)
	s_waitcnt lgkmcnt(0)
	s_barrier
	s_setprio 1
	s_waitcnt lgkmcnt(0)
	v_mfma_f32_16x16x32_bf16 v[64:67], v[24:27], v[178:181], v[64:67]
	v_mfma_f32_16x16x32_bf16 v[64:67], v[28:31], v[182:185], v[64:67]
	v_mfma_f32_16x16x32_bf16 v[68:71], v[112:115], v[178:181], v[68:71]
	v_mfma_f32_16x16x32_bf16 v[68:71], v[116:119], v[182:185], v[68:71]
	v_mfma_f32_16x16x32_bf16 v[72:75], v[24:27], v[186:189], v[72:75]
	v_mfma_f32_16x16x32_bf16 v[72:75], v[28:31], v[190:193], v[72:75]
	v_mfma_f32_16x16x32_bf16 v[76:79], v[112:115], v[186:189], v[76:79]
	v_mfma_f32_16x16x32_bf16 v[76:79], v[116:119], v[190:193], v[76:79]
	v_mfma_f32_16x16x32_bf16 v[80:83], v[24:27], v[194:197], v[80:83]
	v_mfma_f32_16x16x32_bf16 v[80:83], v[28:31], v[198:201], v[80:83]
	v_mfma_f32_16x16x32_bf16 v[84:87], v[112:115], v[194:197], v[84:87]
	v_mfma_f32_16x16x32_bf16 v[84:87], v[116:119], v[198:201], v[84:87]
	v_mfma_f32_16x16x32_bf16 v[88:91], v[24:27], v[202:205], v[88:91]
	v_mfma_f32_16x16x32_bf16 v[88:91], v[28:31], v[206:209], v[88:91]
	v_mfma_f32_16x16x32_bf16 v[92:95], v[112:115], v[202:205], v[92:95]
	v_mfma_f32_16x16x32_bf16 v[92:95], v[116:119], v[206:209], v[92:95]
	s_setprio 0
	s_setprio 1
	v_mfma_f32_16x16x32_bf16 v[96:99], v[120:123], v[178:181], v[96:99]
	v_mfma_f32_16x16x32_bf16 v[96:99], v[124:127], v[182:185], v[96:99]
	v_mfma_f32_16x16x32_bf16 v[32:35], v[170:173], v[178:181], v[32:35]
	v_mfma_f32_16x16x32_bf16 v[32:35], v[174:177], v[182:185], v[32:35]
	v_mfma_f32_16x16x32_bf16 v[36:39], v[120:123], v[186:189], v[36:39]
	v_mfma_f32_16x16x32_bf16 v[36:39], v[124:127], v[190:193], v[36:39]
	v_mfma_f32_16x16x32_bf16 v[40:43], v[170:173], v[186:189], v[40:43]
	v_mfma_f32_16x16x32_bf16 v[40:43], v[174:177], v[190:193], v[40:43]
	v_mfma_f32_16x16x32_bf16 v[44:47], v[120:123], v[194:197], v[44:47]
	v_mfma_f32_16x16x32_bf16 v[44:47], v[124:127], v[198:201], v[44:47]
	v_mfma_f32_16x16x32_bf16 v[48:51], v[170:173], v[194:197], v[48:51]
	v_mfma_f32_16x16x32_bf16 v[48:51], v[174:177], v[198:201], v[48:51]
	v_mfma_f32_16x16x32_bf16 v[52:55], v[120:123], v[202:205], v[52:55]
	v_mfma_f32_16x16x32_bf16 v[52:55], v[124:127], v[206:209], v[52:55]
	v_mfma_f32_16x16x32_bf16 v[56:59], v[170:173], v[202:205], v[56:59]
	v_mfma_f32_16x16x32_bf16 v[56:59], v[174:177], v[206:209], v[56:59]
	s_setprio 0
	s_barrier
; #define PG8_STAGE(bufoff, gbase, voff) do { _Pragma("unroll") for (int _i = 0; _i < 2; ++_i) \
;         __builtin_amdgcn_global_load_lds((const unsigned*)((const char*)(gbase) + (voff)[_i]), (PG8_LAS unsigned*)(lds + (bufoff) + ldsw + _i * 8192), 16, 0, 0); } while (0)
; #define PG8_LDA(dst, b, h) do { _Pragma("unroll") for (int m = 0; m < 4; ++m) _Pragma("unroll") for (int k = 0; k < 2; ++k) dst[m][k] = *(const PG8_LAS bf16x8*)(lds + PG8_SA(b, h) + aoff + m * 2048 + k * 1024); } while (0)
; #define PG8_LDB(dst, b, h) do { _Pragma("unroll") for (int n = 0; n < 2; ++n) _Pragma("unroll") for (int k = 0; k < 2; ++k) dst[n][k] = *(const PG8_LAS bf16x8*)(lds + PG8_SB(b, h) + boff + n * 2048 + k * 1024); } while (0)
; #define PG8_MMA(ai, bj, At, Bt) do { __builtin_amdgcn_s_setprio(1); _Pragma("unroll") for (int m = 0; m < 4; ++m) _Pragma("unroll") for (int n = 0; n < 2; ++n) _Pragma("unroll") for (int k = 0; k < 2; ++k) \
;         acc[ai][bj][m][n] = __builtin_amdgcn_mfma_f32_16x16x32_bf16(Bt[n][k], At[m][k], acc[ai][bj][m][n], 0, 0, 0); __builtin_amdgcn_s_setprio(0); } while (0)
; #define PG8_WAIT_V(n) asm volatile("s_waitcnt vmcnt(" #n ")" ::: "memory")
; #define PG8_WAIT_L(n) asm volatile("s_waitcnt lgkmcnt(" #n ")" ::: "memory")
; #define PG8_BAR __builtin_amdgcn_s_barrier()
; #define PG8_SCHED __builtin_amdgcn_sched_barrier(0)
;     ...
;             PG8_LDB(B0, 0, 0); PG8_LDB(B1, 0, 1); PG8_SCHED; PG8_LDA(At, 0, 0); PG8_STAGE(PG8_SA(1, 1), a1 + hstepA, voffA);
;             PG8_WAIT_V(8); PG8_WAIT_L(0); PG8_BAR; PG8_MMA(0, 0, At, B0); PG8_MMA(0, 1, At, B1); PG8_BAR; PG8_SCHED;
;             PG8_LDA(At, 0, 1); PG8_STAGE(PG8_SB(0, 0), b2, voffB); PG8_STAGE(PG8_SB(0, 1), b2 + hstepB, voffB); PG8_STAGE(PG8_SA(0, 0), a2, voffA);
;             PG8_WAIT_V(8); PG8_WAIT_L(0); PG8_BAR; PG8_MMA(1, 0, At, B0); PG8_MMA(1, 1, At, B1); PG8_BAR; PG8_SCHED;
;             PG8_LDB(B0, 1, 0); PG8_LDB(B1, 1, 1); PG8_SCHED; PG8_LDA(At, 1, 0); PG8_STAGE(PG8_SA(0, 1), a2 + hstepA, voffA);
;             PG8_WAIT_V(8); PG8_WAIT_L(0); PG8_BAR; PG8_MMA(0, 0, At, B0); PG8_MMA(0, 1, At, B1); PG8_BAR; PG8_SCHED;
;             PG8_LDA(At, 1, 1); PG8_STAGE(PG8_SB(1, 0), b3, voffB); PG8_STAGE(PG8_SB(1, 1), b3 + hstepB, voffB); PG8_STAGE(PG8_SA(1, 0), a3, voffA);
;             PG8_WAIT_V(8); PG8_WAIT_L(0); PG8_BAR; PG8_MMA(1, 0, At, B0); PG8_MMA(1, 1, At, B1); PG8_BAR; PG8_SCHED;
	s_mov_b32 m0, s53
	v_lshl_add_u64 v[210:211], v[210:211], 0, s[18:19]
	s_add_u32 s30, s30, 0x10180
	ds_read_b128 v[178:181], v143 offset:49152
	ds_read_b128 v[182:185], v143 offset:50176
	ds_read_b128 v[186:189], v143 offset:51200
	ds_read_b128 v[190:193], v143 offset:52224
	ds_read_b128 v[194:197], v143 offset:53248
	ds_read_b128 v[198:201], v143 offset:54272
	ds_read_b128 v[202:205], v143 offset:55296
	ds_read_b128 v[206:209], v143 offset:56320
	global_load_lds_dwordx4 v[210:211], off
	v_lshl_add_u64 v[210:211], v[212:213], 0, s[18:19]
	s_mov_b32 m0, s54
	s_addc_u32 s31, s31, 0
	global_load_lds_dwordx4 v[210:211], off
	s_mov_b32 m0, s55
	s_nop 0
	global_load_lds_dwordx4 v132, s[30:31]
	s_mov_b32 m0, s56
	s_nop 0
	global_load_lds_dwordx4 v128, s[30:31]
	s_mov_b32 m0, s42
	s_nop 0
	global_load_lds_dwordx4 v134, s[34:35]
	s_mov_b32 m0, s43
	s_nop 0
	global_load_lds_dwordx4 v130, s[34:35]
	s_waitcnt vmcnt(8)
	s_waitcnt lgkmcnt(0)
	s_barrier
	s_setprio 1
	s_waitcnt lgkmcnt(0)
	v_mfma_f32_16x16x32_bf16 v[0:3], v[24:27], v[202:205], v[0:3]
	v_mfma_f32_16x16x32_bf16 v[0:3], v[28:31], v[206:209], v[0:3]
	v_mfma_f32_16x16x32_bf16 v[4:7], v[112:115], v[202:205], v[4:7]
	v_mfma_f32_16x16x32_bf16 v[4:7], v[116:119], v[206:209], v[4:7]
	v_mfma_f32_16x16x32_bf16 v[146:149], v[24:27], v[178:181], v[146:149]
	v_mfma_f32_16x16x32_bf16 v[146:149], v[28:31], v[182:185], v[146:149]
	v_mfma_f32_16x16x32_bf16 v[150:153], v[112:115], v[178:181], v[150:153]
	v_mfma_f32_16x16x32_bf16 v[150:153], v[116:119], v[182:185], v[150:153]
	v_mfma_f32_16x16x32_bf16 v[154:157], v[24:27], v[186:189], v[154:157]
	v_mfma_f32_16x16x32_bf16 v[154:157], v[28:31], v[190:193], v[154:157]
	v_mfma_f32_16x16x32_bf16 v[158:161], v[112:115], v[186:189], v[158:161]
	v_mfma_f32_16x16x32_bf16 v[158:161], v[116:119], v[190:193], v[158:161]
	v_mfma_f32_16x16x32_bf16 v[162:165], v[24:27], v[194:197], v[162:165]
	v_mfma_f32_16x16x32_bf16 v[162:165], v[28:31], v[198:201], v[162:165]
	v_mfma_f32_16x16x32_bf16 v[166:169], v[112:115], v[194:197], v[166:169]
	v_mfma_f32_16x16x32_bf16 v[166:169], v[116:119], v[198:201], v[166:169]
	s_setprio 0
	s_setprio 1
	v_mfma_f32_16x16x32_bf16 v[8:11], v[120:123], v[178:181], v[8:11]
	v_mfma_f32_16x16x32_bf16 v[12:15], v[170:173], v[178:181], v[12:15]
	v_mfma_f32_16x16x32_bf16 v[24:27], v[120:123], v[186:189], v[60:63]
	v_mfma_f32_16x16x32_bf16 v[28:31], v[170:173], v[186:189], v[100:103]
	v_mfma_f32_16x16x32_bf16 v[60:63], v[120:123], v[194:197], v[104:107]
	v_mfma_f32_16x16x32_bf16 v[100:103], v[170:173], v[194:197], v[108:111]
	v_mfma_f32_16x16x32_bf16 v[16:19], v[120:123], v[202:205], v[16:19]
	v_mfma_f32_16x16x32_bf16 v[20:23], v[170:173], v[202:205], v[20:23]
	v_mfma_f32_16x16x32_bf16 v[8:11], v[124:127], v[182:185], v[8:11]
	v_mfma_f32_16x16x32_bf16 v[12:15], v[174:177], v[182:185], v[12:15]
	v_mfma_f32_16x16x32_bf16 v[24:27], v[124:127], v[190:193], v[24:27]
	v_mfma_f32_16x16x32_bf16 v[28:31], v[174:177], v[190:193], v[28:31]
	v_mfma_f32_16x16x32_bf16 v[60:63], v[124:127], v[198:201], v[60:63]
	v_mfma_f32_16x16x32_bf16 v[100:103], v[174:177], v[198:201], v[100:103]
	v_mfma_f32_16x16x32_bf16 v[16:19], v[124:127], v[206:209], v[16:19]
	v_mfma_f32_16x16x32_bf16 v[20:23], v[174:177], v[206:209], v[20:23]
	s_setprio 0
	s_barrier
	ds_read_b128 v[104:107], v141
	ds_read_b128 v[108:111], v141 offset:1024
	ds_read_b128 v[112:115], v141 offset:2048
	ds_read_b128 v[116:119], v141 offset:3072
	ds_read_b128 v[120:123], v142
	ds_read_b128 v[124:127], v142 offset:1024
	ds_read_b128 v[170:173], v142 offset:2048
	ds_read_b128 v[174:177], v142 offset:3072
	s_add_u32 s30, s28, 0x8000
	s_addc_u32 s31, s29, 0
	s_add_u32 s26, s26, 0x1c000
	s_addc_u32 s27, s27, 0
	s_mov_b32 m0, s46
	ds_read_b128 v[178:181], v143
	ds_read_b128 v[182:185], v143 offset:1024
	ds_read_b128 v[186:189], v143 offset:2048
	ds_read_b128 v[190:193], v143 offset:3072
	ds_read_b128 v[194:197], v143 offset:4096
	ds_read_b128 v[198:201], v143 offset:5120
	ds_read_b128 v[202:205], v143 offset:6144
	ds_read_b128 v[206:209], v143 offset:7168
	global_load_lds_dwordx4 v134, s[26:27]
	v_lshl_add_u64 v[210:211], s[26:27], 0, v[130:131]
	s_mov_b32 m0, s47
	s_nop 0
	global_load_lds_dwordx4 v[210:211], off
	s_waitcnt vmcnt(8)
	s_waitcnt lgkmcnt(0)
	s_barrier
	s_setprio 1
	s_waitcnt lgkmcnt(0)
	v_mfma_f32_16x16x32_bf16 v[64:67], v[104:107], v[178:181], v[64:67]
	v_mfma_f32_16x16x32_bf16 v[68:71], v[112:115], v[178:181], v[68:71]
	v_mfma_f32_16x16x32_bf16 v[72:75], v[104:107], v[186:189], v[72:75]
	v_mfma_f32_16x16x32_bf16 v[76:79], v[112:115], v[186:189], v[76:79]
	v_mfma_f32_16x16x32_bf16 v[80:83], v[104:107], v[194:197], v[80:83]
	v_mfma_f32_16x16x32_bf16 v[84:87], v[112:115], v[194:197], v[84:87]
	v_mfma_f32_16x16x32_bf16 v[88:91], v[104:107], v[202:205], v[88:91]
	v_mfma_f32_16x16x32_bf16 v[64:67], v[108:111], v[182:185], v[64:67]
	v_mfma_f32_16x16x32_bf16 v[68:71], v[116:119], v[182:185], v[68:71]
	v_mfma_f32_16x16x32_bf16 v[72:75], v[108:111], v[190:193], v[72:75]
	v_mfma_f32_16x16x32_bf16 v[76:79], v[116:119], v[190:193], v[76:79]
	v_mfma_f32_16x16x32_bf16 v[80:83], v[108:111], v[198:201], v[80:83]
	v_mfma_f32_16x16x32_bf16 v[84:87], v[116:119], v[198:201], v[84:87]
	v_mfma_f32_16x16x32_bf16 v[210:213], v[108:111], v[206:209], v[88:91]
	v_mfma_f32_16x16x32_bf16 v[88:91], v[112:115], v[202:205], v[92:95]
	v_mfma_f32_16x16x32_bf16 v[214:217], v[116:119], v[206:209], v[88:91]
	s_setprio 0
	s_setprio 1
	v_mfma_f32_16x16x32_bf16 v[88:91], v[120:123], v[178:181], v[96:99]
	v_mfma_f32_16x16x32_bf16 v[32:35], v[170:173], v[178:181], v[32:35]
	v_mfma_f32_16x16x32_bf16 v[36:39], v[120:123], v[186:189], v[36:39]
	v_mfma_f32_16x16x32_bf16 v[40:43], v[170:173], v[186:189], v[40:43]
	v_mfma_f32_16x16x32_bf16 v[44:47], v[120:123], v[194:197], v[44:47]
	v_mfma_f32_16x16x32_bf16 v[48:51], v[170:173], v[194:197], v[48:51]
	v_mfma_f32_16x16x32_bf16 v[52:55], v[120:123], v[202:205], v[52:55]
	v_mfma_f32_16x16x32_bf16 v[56:59], v[170:173], v[202:205], v[56:59]
	v_mfma_f32_16x16x32_bf16 v[96:99], v[124:127], v[182:185], v[88:91]
	v_mfma_f32_16x16x32_bf16 v[32:35], v[174:177], v[182:185], v[32:35]
	v_mfma_f32_16x16x32_bf16 v[36:39], v[124:127], v[190:193], v[36:39]
	v_mfma_f32_16x16x32_bf16 v[40:43], v[174:177], v[190:193], v[40:43]
	v_mfma_f32_16x16x32_bf16 v[44:47], v[124:127], v[198:201], v[44:47]
	v_mfma_f32_16x16x32_bf16 v[48:51], v[174:177], v[198:201], v[48:51]
	v_mfma_f32_16x16x32_bf16 v[52:55], v[124:127], v[206:209], v[52:55]
	v_mfma_f32_16x16x32_bf16 v[56:59], v[174:177], v[206:209], v[56:59]
	s_setprio 0
	s_barrier
; #define PG8_STAGE(bufoff, gbase, voff) do { _Pragma("unroll") for (int _i = 0; _i < 2; ++_i) \
;         __builtin_amdgcn_global_load_lds((const unsigned*)((const char*)(gbase) + (voff)[_i]), (PG8_LAS unsigned*)(lds + (bufoff) + ldsw + _i * 8192), 16, 0, 0); } while (0)
; #define PG8_LDA(dst, b, h) do { _Pragma("unroll") for (int m = 0; m < 4; ++m) _Pragma("unroll") for (int k = 0; k < 2; ++k) dst[m][k] = *(const PG8_LAS bf16x8*)(lds + PG8_SA(b, h) + aoff + m * 2048 + k * 1024); } while (0)
; #define PG8_LDB(dst, b, h) do { _Pragma("unroll") for (int n = 0; n < 2; ++n) _Pragma("unroll") for (int k = 0; k < 2; ++k) dst[n][k] = *(const PG8_LAS bf16x8*)(lds + PG8_SB(b, h) + boff + n * 2048 + k * 1024); } while (0)
; #define PG8_MMA(ai, bj, At, Bt) do { __builtin_amdgcn_s_setprio(1); _Pragma("unroll") for (int m = 0; m < 4; ++m) _Pragma("unroll") for (int n = 0; n < 2; ++n) _Pragma("unroll") for (int k = 0; k < 2; ++k) \
;         acc[ai][bj][m][n] = __builtin_amdgcn_mfma_f32_16x16x32_bf16(Bt[n][k], At[m][k], acc[ai][bj][m][n], 0, 0, 0); __builtin_amdgcn_s_setprio(0); } while (0)
; #define PG8_WAIT_V(n) asm volatile("s_waitcnt vmcnt(" #n ")" ::: "memory")
; #define PG8_WAIT_L(n) asm volatile("s_waitcnt lgkmcnt(" #n ")" ::: "memory")
; #define PG8_BAR __builtin_amdgcn_s_barrier()
; #define PG8_SCHED __builtin_amdgcn_sched_barrier(0)
;     ...
;             PG8_WAIT_V(8); PG8_WAIT_L(0); PG8_BAR; PG8_MMA(0, 0, At, B0); PG8_MMA(0, 1, At, B1); PG8_BAR; PG8_SCHED;
;             PG8_LDA(At, 0, 1); PG8_STAGE(PG8_SB(0, 0), b2, voffB); PG8_STAGE(PG8_SB(0, 1), b2 + hstepB, voffB); PG8_STAGE(PG8_SA(0, 0), a2, voffA);
;             PG8_WAIT_V(8); PG8_WAIT_L(0); PG8_BAR; PG8_MMA(1, 0, At, B0); PG8_MMA(1, 1, At, B1); PG8_BAR; PG8_SCHED;
;             PG8_LDB(B0, 1, 0); PG8_LDB(B1, 1, 1); PG8_SCHED; PG8_LDA(At, 1, 0); PG8_STAGE(PG8_SA(0, 1), a2 + hstepA, voffA);
;             PG8_WAIT_V(8); PG8_WAIT_L(0); PG8_BAR; PG8_MMA(0, 0, At, B0); PG8_MMA(0, 1, At, B1); PG8_BAR; PG8_SCHED;
	s_mov_b32 m0, s48
	v_lshl_add_u64 v[246:247], s[24:25], 0, v[132:133]
	s_add_u32 s26, s24, 0x10000
	ds_read_b128 v[88:91], v143 offset:16384
	ds_read_b128 v[92:95], v143 offset:17408
	ds_read_b128 v[178:181], v143 offset:18432
	ds_read_b128 v[182:185], v143 offset:19456
	ds_read_b128 v[186:189], v143 offset:20480
	ds_read_b128 v[190:193], v143 offset:21504
	ds_read_b128 v[194:197], v143 offset:22528
	ds_read_b128 v[198:201], v143 offset:23552
	global_load_lds_dwordx4 v[246:247], off
	v_lshl_add_u64 v[248:249], s[24:25], 0, v[128:129]
	s_mov_b32 m0, s50
	s_addc_u32 s27, s25, 0
	global_load_lds_dwordx4 v[248:249], off
	s_mov_b32 m0, s51
	s_nop 0
	global_load_lds_dwordx4 v132, s[26:27]
	s_mov_b32 m0, s52
	s_nop 0
	global_load_lds_dwordx4 v128, s[26:27]
	s_mov_b32 m0, s23
	s_nop 0
	global_load_lds_dwordx4 v134, s[28:29]
	v_lshl_add_u64 v[202:203], s[28:29], 0, v[130:131]
	s_mov_b32 m0, s37
	s_nop 0
	global_load_lds_dwordx4 v[202:203], off
	s_waitcnt vmcnt(8)
	s_waitcnt lgkmcnt(0)
	s_barrier
	s_setprio 1
	s_waitcnt lgkmcnt(0)
	v_mfma_f32_16x16x32_bf16 v[0:3], v[104:107], v[194:197], v[0:3]
	v_mfma_f32_16x16x32_bf16 v[0:3], v[108:111], v[198:201], v[0:3]
	v_mfma_f32_16x16x32_bf16 v[4:7], v[112:115], v[194:197], v[4:7]
	v_mfma_f32_16x16x32_bf16 v[4:7], v[116:119], v[198:201], v[4:7]
	v_mfma_f32_16x16x32_bf16 v[146:149], v[104:107], v[88:91], v[146:149]
	v_mfma_f32_16x16x32_bf16 v[146:149], v[108:111], v[92:95], v[146:149]
	v_mfma_f32_16x16x32_bf16 v[150:153], v[112:115], v[88:91], v[150:153]
	v_mfma_f32_16x16x32_bf16 v[150:153], v[116:119], v[92:95], v[150:153]
	v_mfma_f32_16x16x32_bf16 v[154:157], v[104:107], v[178:181], v[154:157]
	v_mfma_f32_16x16x32_bf16 v[154:157], v[108:111], v[182:185], v[154:157]
	v_mfma_f32_16x16x32_bf16 v[158:161], v[112:115], v[178:181], v[158:161]
	v_mfma_f32_16x16x32_bf16 v[158:161], v[116:119], v[182:185], v[158:161]
	v_mfma_f32_16x16x32_bf16 v[162:165], v[104:107], v[186:189], v[162:165]
	v_mfma_f32_16x16x32_bf16 v[162:165], v[108:111], v[190:193], v[162:165]
	v_mfma_f32_16x16x32_bf16 v[166:169], v[112:115], v[186:189], v[166:169]
	v_mfma_f32_16x16x32_bf16 v[166:169], v[116:119], v[190:193], v[166:169]
	s_setprio 0
	s_setprio 1
	v_mfma_f32_16x16x32_bf16 v[8:11], v[120:123], v[88:91], v[8:11]
	v_mfma_f32_16x16x32_bf16 v[202:205], v[124:127], v[92:95], v[8:11]
	v_mfma_f32_16x16x32_bf16 v[8:11], v[170:173], v[88:91], v[12:15]
	v_mfma_f32_16x16x32_bf16 v[206:209], v[174:177], v[92:95], v[8:11]
	v_mfma_f32_16x16x32_bf16 v[8:11], v[120:123], v[178:181], v[24:27]
	v_mfma_f32_16x16x32_bf16 v[218:221], v[124:127], v[182:185], v[8:11]
	v_mfma_f32_16x16x32_bf16 v[8:11], v[170:173], v[178:181], v[28:31]
	v_mfma_f32_16x16x32_bf16 v[178:181], v[174:177], v[182:185], v[8:11]
	v_mfma_f32_16x16x32_bf16 v[8:11], v[120:123], v[186:189], v[60:63]
	v_mfma_f32_16x16x32_bf16 v[182:185], v[124:127], v[190:193], v[8:11]
	v_mfma_f32_16x16x32_bf16 v[8:11], v[170:173], v[186:189], v[100:103]
	v_mfma_f32_16x16x32_bf16 v[186:189], v[174:177], v[190:193], v[8:11]
	v_mfma_f32_16x16x32_bf16 v[8:11], v[120:123], v[194:197], v[16:19]
	v_mfma_f32_16x16x32_bf16 v[190:193], v[124:127], v[198:201], v[8:11]
	v_mfma_f32_16x16x32_bf16 v[8:11], v[170:173], v[194:197], v[20:23]
	v_mfma_f32_16x16x32_bf16 v[170:173], v[174:177], v[198:201], v[8:11]
	s_setprio 0
	s_barrier
	s_nop 4
	ds_read_b128 v[8:11], v144
	ds_read_b128 v[12:15], v144 offset:1024
	ds_read_b128 v[16:19], v144 offset:2048
	ds_read_b128 v[20:23], v144 offset:3072
	ds_read_b128 v[174:177], v145
	ds_read_b128 v[194:197], v145 offset:1024
	ds_read_b128 v[198:201], v145 offset:2048
	ds_read_b128 v[222:225], v145 offset:3072
	s_add_u32 s26, s28, 0x4000
	s_addc_u32 s27, s29, 0
	s_mov_b32 m0, s39
	ds_read_b128 v[24:27], v143 offset:32768
	ds_read_b128 v[28:31], v143 offset:33792
	ds_read_b128 v[60:63], v143 offset:34816
	ds_read_b128 v[226:229], v143 offset:35840
	ds_read_b128 v[230:233], v143 offset:36864
	ds_read_b128 v[234:237], v143 offset:37888
	ds_read_b128 v[238:241], v143 offset:38912
	ds_read_b128 v[242:245], v143 offset:39936
	global_load_lds_dwordx4 v134, s[26:27]
	v_lshl_add_u64 v[88:89], s[26:27], 0, v[130:131]
	s_mov_b32 m0, s40
	s_nop 0
	global_load_lds_dwordx4 v[88:89], off
	s_waitcnt vmcnt(8)
	s_waitcnt lgkmcnt(0)
	s_barrier
; #define PG8_STAGE(bufoff, gbase, voff) do { _Pragma("unroll") for (int _i = 0; _i < 2; ++_i) \
;         __builtin_amdgcn_global_load_lds((const unsigned*)((const char*)(gbase) + (voff)[_i]), (PG8_LAS unsigned*)(lds + (bufoff) + ldsw + _i * 8192), 16, 0, 0); } while (0)
; #define PG8_LDA(dst, b, h) do { _Pragma("unroll") for (int m = 0; m < 4; ++m) _Pragma("unroll") for (int k = 0; k < 2; ++k) dst[m][k] = *(const PG8_LAS bf16x8*)(lds + PG8_SA(b, h) + aoff + m * 2048 + k * 1024); } while (0)
; #define PG8_MMA(ai, bj, At, Bt) do { __builtin_amdgcn_s_setprio(1); _Pragma("unroll") for (int m = 0; m < 4; ++m) _Pragma("unroll") for (int n = 0; n < 2; ++n) _Pragma("unroll") for (int k = 0; k < 2; ++k) \
;         acc[ai][bj][m][n] = __builtin_amdgcn_mfma_f32_16x16x32_bf16(Bt[n][k], At[m][k], acc[ai][bj][m][n], 0, 0, 0); __builtin_amdgcn_s_setprio(0); } while (0)
; #define PG8_WAIT_V(n) asm volatile("s_waitcnt vmcnt(" #n ")" ::: "memory")
; #define PG8_WAIT_L(n) asm volatile("s_waitcnt lgkmcnt(" #n ")" ::: "memory")
; #define PG8_BAR __builtin_amdgcn_s_barrier()
; #define PG8_SCHED __builtin_amdgcn_sched_barrier(0)
;     ...
;             PG8_WAIT_V(8); PG8_WAIT_L(0); PG8_BAR; PG8_MMA(0, 0, At, B0); PG8_MMA(0, 1, At, B1); PG8_BAR; PG8_SCHED;
;             PG8_LDA(At, 1, 1); PG8_STAGE(PG8_SB(1, 0), b3, voffB); PG8_STAGE(PG8_SB(1, 1), b3 + hstepB, voffB); PG8_STAGE(PG8_SA(1, 0), a3, voffA);
;             PG8_WAIT_V(8); PG8_WAIT_L(0); PG8_BAR; PG8_MMA(1, 0, At, B0); PG8_MMA(1, 1, At, B1); PG8_BAR; PG8_SCHED;
;     ...
;         if constexpr (ALIGN_EPI) { if (wr == 0) PG8_BAR; }
	s_setprio 1
	s_waitcnt lgkmcnt(0)
	v_mfma_f32_16x16x32_bf16 v[64:67], v[8:11], v[24:27], v[64:67]
	v_mfma_f32_16x16x32_bf16 v[124:127], v[12:15], v[28:31], v[64:67]
	v_mfma_f32_16x16x32_bf16 v[64:67], v[16:19], v[24:27], v[68:71]
	v_mfma_f32_16x16x32_bf16 v[120:123], v[20:23], v[28:31], v[64:67]
	v_mfma_f32_16x16x32_bf16 v[64:67], v[8:11], v[60:63], v[72:75]
	v_mfma_f32_16x16x32_bf16 v[108:111], v[12:15], v[226:229], v[64:67]
	v_mfma_f32_16x16x32_bf16 v[64:67], v[16:19], v[60:63], v[76:79]
	v_mfma_f32_16x16x32_bf16 v[104:107], v[20:23], v[226:229], v[64:67]
	v_mfma_f32_16x16x32_bf16 v[64:67], v[8:11], v[230:233], v[80:83]
	v_mfma_f32_16x16x32_bf16 v[92:95], v[12:15], v[234:237], v[64:67]
	v_mfma_f32_16x16x32_bf16 v[64:67], v[16:19], v[230:233], v[84:87]
	v_mfma_f32_16x16x32_bf16 v[88:91], v[20:23], v[234:237], v[64:67]
	v_mfma_f32_16x16x32_bf16 v[64:67], v[8:11], v[238:241], v[210:213]
	v_mfma_f32_16x16x32_bf16 v[76:79], v[12:15], v[242:245], v[64:67]
	v_mfma_f32_16x16x32_bf16 v[64:67], v[16:19], v[238:241], v[214:217]
	v_mfma_f32_16x16x32_bf16 v[72:75], v[20:23], v[242:245], v[64:67]
	s_setprio 0
	s_setprio 1
	v_mfma_f32_16x16x32_bf16 v[64:67], v[174:177], v[24:27], v[96:99]
	v_mfma_f32_16x16x32_bf16 v[24:27], v[198:201], v[24:27], v[32:35]
	v_mfma_f32_16x16x32_bf16 v[112:115], v[222:225], v[28:31], v[24:27]
	v_mfma_f32_16x16x32_bf16 v[24:27], v[174:177], v[60:63], v[36:39]
	v_mfma_f32_16x16x32_bf16 v[100:103], v[194:197], v[226:229], v[24:27]
	v_mfma_f32_16x16x32_bf16 v[24:27], v[198:201], v[60:63], v[40:43]
	v_mfma_f32_16x16x32_bf16 v[96:99], v[222:225], v[226:229], v[24:27]
	v_mfma_f32_16x16x32_bf16 v[24:27], v[174:177], v[230:233], v[44:47]
	v_mfma_f32_16x16x32_bf16 v[84:87], v[194:197], v[234:237], v[24:27]
	v_mfma_f32_16x16x32_bf16 v[24:27], v[198:201], v[230:233], v[48:51]
	v_mfma_f32_16x16x32_bf16 v[80:83], v[222:225], v[234:237], v[24:27]
	v_mfma_f32_16x16x32_bf16 v[24:27], v[174:177], v[238:241], v[52:55]
	v_mfma_f32_16x16x32_bf16 v[60:63], v[194:197], v[242:245], v[24:27]
	v_mfma_f32_16x16x32_bf16 v[24:27], v[198:201], v[238:241], v[56:59]
	v_mfma_f32_16x16x32_bf16 v[116:119], v[194:197], v[28:31], v[64:67]
	v_mfma_f32_16x16x32_bf16 v[56:59], v[222:225], v[242:245], v[24:27]
	s_setprio 0
	s_barrier
	s_mov_b32 m0, s53
	s_nop 2
	v_lshl_add_u64 v[24:25], v[246:247], 0, s[12:13]
	s_add_u32 s24, s24, 0x10080
	ds_read_b128 v[32:35], v143 offset:49152
	ds_read_b128 v[36:39], v143 offset:50176
	ds_read_b128 v[210:213], v143 offset:51200
	ds_read_b128 v[214:217], v143 offset:52224
	ds_read_b128 v[226:229], v143 offset:53248
	ds_read_b128 v[230:233], v143 offset:54272
	ds_read_b128 v[234:237], v143 offset:55296
	ds_read_b128 v[238:241], v143 offset:56320
	global_load_lds_dwordx4 v[24:25], off
	v_lshl_add_u64 v[24:25], v[248:249], 0, s[12:13]
	s_mov_b32 m0, s54
	s_addc_u32 s25, s25, 0
	global_load_lds_dwordx4 v[24:25], off
	s_mov_b32 m0, s55
	s_nop 0
	global_load_lds_dwordx4 v132, s[24:25]
	s_mov_b32 m0, s56
	s_nop 0
	global_load_lds_dwordx4 v128, s[24:25]
	s_mov_b32 m0, s42
	s_nop 0
	global_load_lds_dwordx4 v134, s[30:31]
	v_lshl_add_u64 v[24:25], s[30:31], 0, v[130:131]
	s_mov_b32 m0, s43
	s_nop 0
	global_load_lds_dwordx4 v[24:25], off
	s_waitcnt vmcnt(8)
	s_waitcnt lgkmcnt(0)
	s_barrier
	s_setprio 1
	s_waitcnt lgkmcnt(0)
	v_mfma_f32_16x16x32_bf16 v[24:27], v[8:11], v[32:35], v[146:149]
	v_mfma_f32_16x16x32_bf16 v[68:71], v[12:15], v[36:39], v[24:27]
	v_mfma_f32_16x16x32_bf16 v[24:27], v[16:19], v[32:35], v[150:153]
	v_mfma_f32_16x16x32_bf16 v[64:67], v[20:23], v[36:39], v[24:27]
	v_mfma_f32_16x16x32_bf16 v[24:27], v[8:11], v[210:213], v[154:157]
	v_mfma_f32_16x16x32_bf16 v[44:47], v[12:15], v[214:217], v[24:27]
	v_mfma_f32_16x16x32_bf16 v[24:27], v[16:19], v[210:213], v[158:161]
	v_mfma_f32_16x16x32_bf16 v[40:43], v[20:23], v[214:217], v[24:27]
	v_mfma_f32_16x16x32_bf16 v[24:27], v[8:11], v[226:229], v[162:165]
	v_mfma_f32_16x16x32_bf16 v[0:3], v[8:11], v[234:237], v[0:3]
	v_mfma_f32_16x16x32_bf16 v[28:31], v[12:15], v[230:233], v[24:27]
	v_mfma_f32_16x16x32_bf16 v[24:27], v[16:19], v[226:229], v[166:169]
	v_mfma_f32_16x16x32_bf16 v[12:15], v[12:15], v[238:241], v[0:3]
	v_mfma_f32_16x16x32_bf16 v[0:3], v[16:19], v[234:237], v[4:7]
	v_mfma_f32_16x16x32_bf16 v[24:27], v[20:23], v[230:233], v[24:27]
	v_mfma_f32_16x16x32_bf16 v[8:11], v[20:23], v[238:241], v[0:3]
	s_setprio 0
	s_setprio 1
	v_mfma_f32_16x16x32_bf16 v[0:3], v[174:177], v[32:35], v[202:205]
	v_mfma_f32_16x16x32_bf16 v[52:55], v[194:197], v[36:39], v[0:3]
	v_mfma_f32_16x16x32_bf16 v[0:3], v[198:201], v[32:35], v[206:209]
	v_mfma_f32_16x16x32_bf16 v[48:51], v[222:225], v[36:39], v[0:3]
	v_mfma_f32_16x16x32_bf16 v[0:3], v[174:177], v[210:213], v[218:221]
	v_mfma_f32_16x16x32_bf16 v[36:39], v[194:197], v[214:217], v[0:3]
	v_mfma_f32_16x16x32_bf16 v[0:3], v[198:201], v[210:213], v[178:181]
	v_mfma_f32_16x16x32_bf16 v[32:35], v[222:225], v[214:217], v[0:3]
	v_mfma_f32_16x16x32_bf16 v[0:3], v[174:177], v[226:229], v[182:185]
	v_mfma_f32_16x16x32_bf16 v[20:23], v[194:197], v[230:233], v[0:3]
	v_mfma_f32_16x16x32_bf16 v[0:3], v[198:201], v[226:229], v[186:189]
	v_mfma_f32_16x16x32_bf16 v[16:19], v[222:225], v[230:233], v[0:3]
	v_mfma_f32_16x16x32_bf16 v[0:3], v[174:177], v[234:237], v[190:193]
	v_mfma_f32_16x16x32_bf16 v[4:7], v[194:197], v[238:241], v[0:3]
	v_mfma_f32_16x16x32_bf16 v[0:3], v[198:201], v[234:237], v[170:173]
	v_mfma_f32_16x16x32_bf16 v[0:3], v[222:225], v[238:241], v[0:3]
	s_setprio 0
	s_barrier
	s_and_b64 vcc, exec, s[0:1]
	s_cbranch_vccnz .LBB0_99
	s_barrier

; #define PG8_STAGE(bufoff, gbase, voff) do { _Pragma("unroll") for (int _i = 0; _i < 2; ++_i) \
;         __builtin_amdgcn_global_load_lds((const unsigned*)((const char*)(gbase) + (voff)[_i]), (PG8_LAS unsigned*)(lds + (bufoff) + ldsw + _i * 8192), 16, 0, 0); } while (0)
; #define PG8_LDA(dst, b, h) do { _Pragma("unroll") for (int m = 0; m < 4; ++m) _Pragma("unroll") for (int k = 0; k < 2; ++k) dst[m][k] = *(const PG8_LAS bf16x8*)(lds + PG8_SA(b, h) + aoff + m * 2048 + k * 1024); } while (0)
; #define PG8_LDB(dst, b, h) do { _Pragma("unroll") for (int n = 0; n < 2; ++n) _Pragma("unroll") for (int k = 0; k < 2; ++k) dst[n][k] = *(const PG8_LAS bf16x8*)(lds + PG8_SB(b, h) + boff + n * 2048 + k * 1024); } while (0)
; #define PG8_MMA(ai, bj, At, Bt) do { __builtin_amdgcn_s_setprio(1); _Pragma("unroll") for (int m = 0; m < 4; ++m) _Pragma("unroll") for (int n = 0; n < 2; ++n) _Pragma("unroll") for (int k = 0; k < 2; ++k) \
;         acc[ai][bj][m][n] = __builtin_amdgcn_mfma_f32_16x16x32_bf16(Bt[n][k], At[m][k], acc[ai][bj][m][n], 0, 0, 0); __builtin_amdgcn_s_setprio(0); } while (0)
; #define PG8_WAIT_V(n) asm volatile("s_waitcnt vmcnt(" #n ")" ::: "memory")
; #define PG8_WAIT_L(n) asm volatile("s_waitcnt lgkmcnt(" #n ")" ::: "memory")
; #define PG8_BAR __builtin_amdgcn_s_barrier()
; #define PG8_SCHED __builtin_amdgcn_sched_barrier(0)
;     ...
;         for (int t = 0; t < nt; t += 2) {
;             const bool last = (t == nt - 2);
;             const char* a1 = cA + (ptrdiff_t)(t + 1) * kstepA;
;             const char* a2 = last ? nA : cA + (ptrdiff_t)(t + 2) * kstepA; const char* b2 = last ? nB : cB + (ptrdiff_t)(t + 2) * kstep;
;             const char* a3 = a2 + kstepA; const char* b3 = b2 + kstep;
;             if (last && has_next) S.a_ready(nxt);
;             if constexpr (SP2) {
;             PG8_LDB(B0, 0, 0); PG8_LDB(B1, 0, 1); PG8_SCHED; PG8_LDA(At, 0, 0); PG8_STAGE(PG8_SA(1, 1), a1 + hstepA, voffA);
;             PG8_WAIT_V(8); PG8_WAIT_L(0); PG8_BAR; PG8_MMA(0, 0, At, B0); PG8_MMA(0, 1, At, B1); PG8_BAR; PG8_SCHED;
;             PG8_LDA(At, 0, 1); PG8_STAGE(PG8_SB(0, 0), b2, voffB); PG8_STAGE(PG8_SB(0, 1), b2 + hstepB, voffB); PG8_STAGE(PG8_SA(0, 0), a2, voffA);
;             PG8_WAIT_V(8); PG8_WAIT_L(0); PG8_BAR; PG8_MMA(1, 0, At, B0); PG8_MMA(1, 1, At, B1); PG8_BAR; PG8_SCHED;
.LBB0_328:
	s_add_u32 s65, s6, 0x4000
	s_addc_u32 s66, s7, 0
	s_cmp_eq_u32 vcc_lo, 28
	s_cselect_b32 s90, s54, s65
	s_cselect_b32 s91, s29, s66
	s_cselect_b32 s88, s55, s56
	s_cselect_b32 s89, s31, s57
	s_add_u32 s86, s90, 0x8000
	s_addc_u32 s87, s91, 0
	s_add_i32 s65, 0, 0x10000
	s_add_i32 s66, 0, 0x14000
	v_add_u32_e32 v22, s65, v182
	v_add_u32_e32 v54, s66, v182
	ds_read_b128 v[10:13], v22
	ds_read_b128 v[14:17], v22 offset:1024
	ds_read_b128 v[18:21], v22 offset:2048
	ds_read_b128 v[22:25], v22 offset:3072
	ds_read_b128 v[26:29], v54
	ds_read_b128 v[38:41], v54 offset:1024
	ds_read_b128 v[50:53], v54 offset:2048
	ds_read_b128 v[54:57], v54 offset:3072
	s_add_i32 m0, s51, 0xc000
	ds_read_b128 v[172:175], v183
	ds_read_b128 v[176:179], v183 offset:1024
	ds_read_b128 v[184:187], v183 offset:2048
	ds_read_b128 v[188:191], v183 offset:3072
	ds_read_b128 v[192:195], v183 offset:4096
	ds_read_b128 v[196:199], v183 offset:5120
	ds_read_b128 v[200:203], v183 offset:6144
	ds_read_b128 v[204:207], v183 offset:7168
	global_load_lds_dwordx4 v168, s[6:7]
	s_add_i32 m0, s51, 0xe000
	s_nop 0
	global_load_lds_dwordx4 v170, s[6:7]
	s_waitcnt vmcnt(8)
	s_waitcnt lgkmcnt(0)
	s_barrier
	s_setprio 1
	s_waitcnt lgkmcnt(0)
	v_mfma_f32_16x16x32_bf16 v[158:161], v[10:13], v[172:175], v[158:161]
	v_mfma_f32_16x16x32_bf16 v[158:161], v[14:17], v[176:179], v[158:161]
	v_mfma_f32_16x16x32_bf16 v[154:157], v[18:21], v[172:175], v[154:157]
	v_mfma_f32_16x16x32_bf16 v[154:157], v[22:25], v[176:179], v[154:157]
	v_mfma_f32_16x16x32_bf16 v[142:145], v[10:13], v[184:187], v[142:145]
	v_mfma_f32_16x16x32_bf16 v[142:145], v[14:17], v[188:191], v[142:145]
	v_mfma_f32_16x16x32_bf16 v[138:141], v[18:21], v[184:187], v[138:141]
	v_mfma_f32_16x16x32_bf16 v[138:141], v[22:25], v[188:191], v[138:141]
	v_mfma_f32_16x16x32_bf16 v[126:129], v[10:13], v[192:195], v[126:129]
	v_mfma_f32_16x16x32_bf16 v[126:129], v[14:17], v[196:199], v[126:129]
	v_mfma_f32_16x16x32_bf16 v[122:125], v[18:21], v[192:195], v[122:125]
	v_mfma_f32_16x16x32_bf16 v[122:125], v[22:25], v[196:199], v[122:125]
	v_mfma_f32_16x16x32_bf16 v[110:113], v[10:13], v[200:203], v[110:113]
	v_mfma_f32_16x16x32_bf16 v[110:113], v[14:17], v[204:207], v[110:113]
	v_mfma_f32_16x16x32_bf16 v[106:109], v[18:21], v[200:203], v[106:109]
	v_mfma_f32_16x16x32_bf16 v[106:109], v[22:25], v[204:207], v[106:109]
	s_setprio 0
	s_setprio 1
	v_mfma_f32_16x16x32_bf16 v[150:153], v[26:29], v[172:175], v[150:153]
	v_mfma_f32_16x16x32_bf16 v[150:153], v[38:41], v[176:179], v[150:153]
	v_mfma_f32_16x16x32_bf16 v[146:149], v[50:53], v[172:175], v[146:149]
	v_mfma_f32_16x16x32_bf16 v[146:149], v[54:57], v[176:179], v[146:149]
	v_mfma_f32_16x16x32_bf16 v[134:137], v[26:29], v[184:187], v[134:137]
	v_mfma_f32_16x16x32_bf16 v[134:137], v[38:41], v[188:191], v[134:137]
	v_mfma_f32_16x16x32_bf16 v[130:133], v[50:53], v[184:187], v[130:133]
	v_mfma_f32_16x16x32_bf16 v[130:133], v[54:57], v[188:191], v[130:133]
	v_mfma_f32_16x16x32_bf16 v[118:121], v[26:29], v[192:195], v[118:121]
	v_mfma_f32_16x16x32_bf16 v[118:121], v[38:41], v[196:199], v[118:121]
	v_mfma_f32_16x16x32_bf16 v[114:117], v[50:53], v[192:195], v[114:117]
	v_mfma_f32_16x16x32_bf16 v[114:117], v[54:57], v[196:199], v[114:117]
	v_mfma_f32_16x16x32_bf16 v[102:105], v[26:29], v[200:203], v[102:105]
	v_mfma_f32_16x16x32_bf16 v[102:105], v[38:41], v[204:207], v[102:105]
	v_mfma_f32_16x16x32_bf16 v[98:101], v[50:53], v[200:203], v[98:101]
	v_mfma_f32_16x16x32_bf16 v[98:101], v[54:57], v[204:207], v[98:101]
	s_setprio 0
	s_barrier
	s_add_i32 s65, s65, s2
	s_mov_b32 m0, s65
	ds_read_b128 v[172:175], v183 offset:16384
	ds_read_b128 v[176:179], v183 offset:17408
	ds_read_b128 v[184:187], v183 offset:18432
	ds_read_b128 v[188:191], v183 offset:19456
	ds_read_b128 v[192:195], v183 offset:20480
	ds_read_b128 v[196:199], v183 offset:21504
	ds_read_b128 v[200:203], v183 offset:22528
	ds_read_b128 v[204:207], v183 offset:23552
	global_load_lds_dwordx4 v0, s[88:89]
	s_add_i32 m0, s65, 0x2000
	s_add_u32 s96, s88, 0x4000
	s_addc_u32 s97, s89, 0
	s_add_i32 s65, s66, s2
	global_load_lds_dwordx4 v162, s[88:89]
	s_mov_b32 m0, s65
	s_nop 0
	global_load_lds_dwordx4 v0, s[96:97]
	s_add_i32 m0, s65, 0x2000
	s_nop 0
	global_load_lds_dwordx4 v162, s[96:97]
	s_mov_b32 m0, s51
	s_nop 0
	global_load_lds_dwordx4 v166, s[90:91]
	s_mov_b32 m0, s92
	s_nop 0
	global_load_lds_dwordx4 v164, s[90:91]
	s_waitcnt vmcnt(8)
	s_waitcnt lgkmcnt(0)
	s_barrier
	s_setprio 1
	s_waitcnt lgkmcnt(0)
	v_mfma_f32_16x16x32_bf16 v[94:97], v[10:13], v[172:175], v[94:97]
	v_mfma_f32_16x16x32_bf16 v[90:93], v[18:21], v[172:175], v[90:93]
	v_mfma_f32_16x16x32_bf16 v[78:81], v[10:13], v[184:187], v[78:81]
	v_mfma_f32_16x16x32_bf16 v[74:77], v[18:21], v[184:187], v[74:77]
	v_mfma_f32_16x16x32_bf16 v[62:65], v[10:13], v[192:195], v[62:65]
	v_mfma_f32_16x16x32_bf16 v[58:61], v[18:21], v[192:195], v[58:61]
	v_mfma_f32_16x16x32_bf16 v[10:13], v[10:13], v[200:203], v[34:37]
	v_mfma_f32_16x16x32_bf16 v[94:97], v[14:17], v[176:179], v[94:97]
	v_mfma_f32_16x16x32_bf16 v[90:93], v[22:25], v[176:179], v[90:93]
	v_mfma_f32_16x16x32_bf16 v[78:81], v[14:17], v[188:191], v[78:81]
	v_mfma_f32_16x16x32_bf16 v[74:77], v[22:25], v[188:191], v[74:77]
	v_mfma_f32_16x16x32_bf16 v[62:65], v[14:17], v[196:199], v[62:65]
	v_mfma_f32_16x16x32_bf16 v[58:61], v[22:25], v[196:199], v[58:61]
	v_mfma_f32_16x16x32_bf16 v[10:13], v[14:17], v[204:207], v[10:13]
	v_mfma_f32_16x16x32_bf16 v[14:17], v[18:21], v[200:203], v[30:33]
	v_mfma_f32_16x16x32_bf16 v[14:17], v[22:25], v[204:207], v[14:17]
	s_setprio 0
	s_setprio 1
	v_mfma_f32_16x16x32_bf16 v[30:33], v[26:29], v[184:187], v[70:73]
	v_mfma_f32_16x16x32_bf16 v[70:73], v[38:41], v[188:191], v[30:33]
	v_mfma_f32_16x16x32_bf16 v[30:33], v[50:53], v[184:187], v[66:69]
	v_mfma_f32_16x16x32_bf16 v[66:69], v[54:57], v[188:191], v[30:33]
	v_mfma_f32_16x16x32_bf16 v[30:33], v[26:29], v[192:195], v[46:49]
	v_mfma_f32_16x16x32_bf16 v[46:49], v[38:41], v[196:199], v[30:33]
	v_mfma_f32_16x16x32_bf16 v[30:33], v[50:53], v[192:195], v[42:45]
	v_mfma_f32_16x16x32_bf16 v[6:9], v[26:29], v[200:203], v[6:9]
	v_mfma_f32_16x16x32_bf16 v[2:5], v[50:53], v[200:203], v[2:5]
	v_mfma_f32_16x16x32_bf16 v[18:21], v[26:29], v[172:175], v[86:89]
	v_mfma_f32_16x16x32_bf16 v[22:25], v[50:53], v[172:175], v[82:85]
	v_mfma_f32_16x16x32_bf16 v[42:45], v[54:57], v[196:199], v[30:33]
	v_mfma_f32_16x16x32_bf16 v[6:9], v[38:41], v[204:207], v[6:9]
	v_mfma_f32_16x16x32_bf16 v[2:5], v[54:57], v[204:207], v[2:5]
	v_mfma_f32_16x16x32_bf16 v[18:21], v[38:41], v[176:179], v[18:21]
	v_mfma_f32_16x16x32_bf16 v[22:25], v[54:57], v[176:179], v[22:25]
	s_setprio 0
	s_barrier
; #define PG8_STAGE(bufoff, gbase, voff) do { _Pragma("unroll") for (int _i = 0; _i < 2; ++_i) \
;         __builtin_amdgcn_global_load_lds((const unsigned*)((const char*)(gbase) + (voff)[_i]), (PG8_LAS unsigned*)(lds + (bufoff) + ldsw + _i * 8192), 16, 0, 0); } while (0)
; #define PG8_LDA(dst, b, h) do { _Pragma("unroll") for (int m = 0; m < 4; ++m) _Pragma("unroll") for (int k = 0; k < 2; ++k) dst[m][k] = *(const PG8_LAS bf16x8*)(lds + PG8_SA(b, h) + aoff + m * 2048 + k * 1024); } while (0)
; #define PG8_LDB(dst, b, h) do { _Pragma("unroll") for (int n = 0; n < 2; ++n) _Pragma("unroll") for (int k = 0; k < 2; ++k) dst[n][k] = *(const PG8_LAS bf16x8*)(lds + PG8_SB(b, h) + boff + n * 2048 + k * 1024); } while (0)
; #define PG8_MMA(ai, bj, At, Bt) do { __builtin_amdgcn_s_setprio(1); _Pragma("unroll") for (int m = 0; m < 4; ++m) _Pragma("unroll") for (int n = 0; n < 2; ++n) _Pragma("unroll") for (int k = 0; k < 2; ++k) \
;         acc[ai][bj][m][n] = __builtin_amdgcn_mfma_f32_16x16x32_bf16(Bt[n][k], At[m][k], acc[ai][bj][m][n], 0, 0, 0); __builtin_amdgcn_s_setprio(0); } while (0)
; #define PG8_WAIT_V(n) asm volatile("s_waitcnt vmcnt(" #n ")" ::: "memory")
; #define PG8_WAIT_L(n) asm volatile("s_waitcnt lgkmcnt(" #n ")" ::: "memory")
; #define PG8_BAR __builtin_amdgcn_s_barrier()
; #define PG8_SCHED __builtin_amdgcn_sched_barrier(0)
;     ...
;             PG8_LDB(B0, 1, 0); PG8_LDB(B1, 1, 1); PG8_SCHED; PG8_LDA(At, 1, 0); PG8_STAGE(PG8_SA(0, 1), a2 + hstepA, voffA);
;             PG8_WAIT_V(8); PG8_WAIT_L(0); PG8_BAR; PG8_MMA(0, 0, At, B0); PG8_MMA(0, 1, At, B1); PG8_BAR; PG8_SCHED;
;             PG8_LDA(At, 1, 1); PG8_STAGE(PG8_SB(1, 0), b3, voffB); PG8_STAGE(PG8_SB(1, 1), b3 + hstepB, voffB); PG8_STAGE(PG8_SA(1, 0), a3, voffA);
;             PG8_WAIT_V(8); PG8_WAIT_L(0); PG8_BAR; PG8_MMA(1, 0, At, B0); PG8_MMA(1, 1, At, B1); PG8_BAR; PG8_SCHED;
	s_add_i32 s65, 0, 0x18000
	v_add_u32_e32 v34, s65, v182
	s_add_i32 s66, 0, 0x1c000
	ds_read_b128 v[26:29], v34
	ds_read_b128 v[30:33], v34 offset:1024
	ds_read_b128 v[38:41], v34 offset:2048
	ds_read_b128 v[50:53], v34 offset:3072
	v_add_u32_e32 v34, s66, v182
	ds_read_b128 v[54:57], v34
	ds_read_b128 v[172:175], v34 offset:1024
	ds_read_b128 v[176:179], v34 offset:2048
	ds_read_b128 v[184:187], v34 offset:3072
	s_add_u32 s90, s90, 0x4000
	s_addc_u32 s91, s91, 0
	s_mov_b32 m0, s14
	ds_read_b128 v[34:37], v183 offset:32768
	ds_read_b128 v[82:85], v183 offset:33792
	ds_read_b128 v[86:89], v183 offset:34816
	ds_read_b128 v[188:191], v183 offset:35840
	ds_read_b128 v[192:195], v183 offset:36864
	ds_read_b128 v[196:199], v183 offset:37888
	ds_read_b128 v[200:203], v183 offset:38912
	ds_read_b128 v[204:207], v183 offset:39936
	global_load_lds_dwordx4 v166, s[90:91]
	v_lshl_add_u64 v[208:209], s[90:91], 0, v[164:165]
	s_mov_b32 m0, s15
	s_nop 0
	global_load_lds_dwordx4 v[208:209], off
	s_waitcnt vmcnt(8)
	s_waitcnt lgkmcnt(0)
	s_barrier
	s_setprio 1
	s_waitcnt lgkmcnt(0)
	v_mfma_f32_16x16x32_bf16 v[158:161], v[26:29], v[34:37], v[158:161]
	v_mfma_f32_16x16x32_bf16 v[158:161], v[30:33], v[82:85], v[158:161]
	v_mfma_f32_16x16x32_bf16 v[154:157], v[38:41], v[34:37], v[154:157]
	v_mfma_f32_16x16x32_bf16 v[154:157], v[50:53], v[82:85], v[154:157]
	v_mfma_f32_16x16x32_bf16 v[142:145], v[26:29], v[86:89], v[142:145]
	v_mfma_f32_16x16x32_bf16 v[142:145], v[30:33], v[188:191], v[142:145]
	v_mfma_f32_16x16x32_bf16 v[138:141], v[38:41], v[86:89], v[138:141]
	v_mfma_f32_16x16x32_bf16 v[138:141], v[50:53], v[188:191], v[138:141]
	v_mfma_f32_16x16x32_bf16 v[126:129], v[26:29], v[192:195], v[126:129]
	v_mfma_f32_16x16x32_bf16 v[126:129], v[30:33], v[196:199], v[126:129]
	v_mfma_f32_16x16x32_bf16 v[122:125], v[38:41], v[192:195], v[122:125]
	v_mfma_f32_16x16x32_bf16 v[122:125], v[50:53], v[196:199], v[122:125]
	v_mfma_f32_16x16x32_bf16 v[110:113], v[26:29], v[200:203], v[110:113]
	v_mfma_f32_16x16x32_bf16 v[110:113], v[30:33], v[204:207], v[110:113]
	v_mfma_f32_16x16x32_bf16 v[106:109], v[38:41], v[200:203], v[106:109]
	v_mfma_f32_16x16x32_bf16 v[106:109], v[50:53], v[204:207], v[106:109]
	s_setprio 0
	s_setprio 1
	v_mfma_f32_16x16x32_bf16 v[150:153], v[54:57], v[34:37], v[150:153]
	v_mfma_f32_16x16x32_bf16 v[34:37], v[176:179], v[34:37], v[146:149]
	v_mfma_f32_16x16x32_bf16 v[146:149], v[184:187], v[82:85], v[34:37]
	v_mfma_f32_16x16x32_bf16 v[34:37], v[54:57], v[86:89], v[134:137]
	v_mfma_f32_16x16x32_bf16 v[134:137], v[172:175], v[188:191], v[34:37]
	v_mfma_f32_16x16x32_bf16 v[34:37], v[176:179], v[86:89], v[130:133]
	v_mfma_f32_16x16x32_bf16 v[130:133], v[184:187], v[188:191], v[34:37]
	v_mfma_f32_16x16x32_bf16 v[34:37], v[54:57], v[192:195], v[118:121]
	v_mfma_f32_16x16x32_bf16 v[118:121], v[172:175], v[196:199], v[34:37]
	v_mfma_f32_16x16x32_bf16 v[34:37], v[176:179], v[192:195], v[114:117]
	v_mfma_f32_16x16x32_bf16 v[114:117], v[184:187], v[196:199], v[34:37]
	v_mfma_f32_16x16x32_bf16 v[34:37], v[54:57], v[200:203], v[102:105]
	v_mfma_f32_16x16x32_bf16 v[102:105], v[172:175], v[204:207], v[34:37]
	v_mfma_f32_16x16x32_bf16 v[34:37], v[176:179], v[200:203], v[98:101]
	v_mfma_f32_16x16x32_bf16 v[150:153], v[172:175], v[82:85], v[150:153]
	v_mfma_f32_16x16x32_bf16 v[98:101], v[184:187], v[204:207], v[34:37]
	s_setprio 0
	s_barrier
	s_add_u32 s90, s88, 0x8000
	s_addc_u32 s91, s89, 0
	s_add_i32 s65, s65, s2
	s_nop 0
	s_mov_b32 m0, s65
	ds_read_b128 v[82:85], v183 offset:49152
	ds_read_b128 v[188:191], v183 offset:50176
	ds_read_b128 v[192:195], v183 offset:51200
	ds_read_b128 v[196:199], v183 offset:52224
	ds_read_b128 v[200:203], v183 offset:53248
	ds_read_b128 v[204:207], v183 offset:54272
	ds_read_b128 v[208:211], v183 offset:55296
	ds_read_b128 v[216:219], v183 offset:56320
	global_load_lds_dwordx4 v0, s[90:91]
	s_add_i32 m0, s65, 0x2000
	s_add_u32 s88, s88, 0xc000
	s_addc_u32 s89, s89, 0
	s_add_i32 s65, s66, s2
	global_load_lds_dwordx4 v162, s[90:91]
	s_mov_b32 m0, s65
	s_nop 0
	global_load_lds_dwordx4 v0, s[88:89]
	s_add_i32 m0, s65, 0x2000
	s_nop 0
	global_load_lds_dwordx4 v162, s[88:89]
	s_mov_b32 m0, s71
	s_nop 0
	global_load_lds_dwordx4 v166, s[86:87]
	v_lshl_add_u64 v[34:35], s[86:87], 0, v[164:165]
	s_mov_b32 m0, s80
	s_nop 0
	global_load_lds_dwordx4 v[34:35], off
	s_waitcnt vmcnt(8)
	s_waitcnt lgkmcnt(0)
	s_barrier
	s_setprio 1
	s_waitcnt lgkmcnt(0)
	v_mfma_f32_16x16x32_bf16 v[34:37], v[26:29], v[82:85], v[94:97]
	v_mfma_f32_16x16x32_bf16 v[94:97], v[30:33], v[188:191], v[34:37]
	v_mfma_f32_16x16x32_bf16 v[34:37], v[38:41], v[82:85], v[90:93]
	v_mfma_f32_16x16x32_bf16 v[90:93], v[50:53], v[188:191], v[34:37]
	v_mfma_f32_16x16x32_bf16 v[34:37], v[26:29], v[192:195], v[78:81]
	v_mfma_f32_16x16x32_bf16 v[78:81], v[30:33], v[196:199], v[34:37]
	v_mfma_f32_16x16x32_bf16 v[34:37], v[38:41], v[192:195], v[74:77]
	v_mfma_f32_16x16x32_bf16 v[74:77], v[50:53], v[196:199], v[34:37]
	v_mfma_f32_16x16x32_bf16 v[34:37], v[26:29], v[200:203], v[62:65]
	v_mfma_f32_16x16x32_bf16 v[62:65], v[30:33], v[204:207], v[34:37]
	v_mfma_f32_16x16x32_bf16 v[34:37], v[38:41], v[200:203], v[58:61]
	v_mfma_f32_16x16x32_bf16 v[10:13], v[26:29], v[208:211], v[10:13]
	v_mfma_f32_16x16x32_bf16 v[58:61], v[50:53], v[204:207], v[34:37]
	v_mfma_f32_16x16x32_bf16 v[34:37], v[30:33], v[216:219], v[10:13]
	v_mfma_f32_16x16x32_bf16 v[10:13], v[38:41], v[208:211], v[14:17]
	v_mfma_f32_16x16x32_bf16 v[30:33], v[50:53], v[216:219], v[10:13]
	s_setprio 0
	s_setprio 1
	v_mfma_f32_16x16x32_bf16 v[10:13], v[54:57], v[82:85], v[18:21]
	v_mfma_f32_16x16x32_bf16 v[86:89], v[172:175], v[188:191], v[10:13]
	v_mfma_f32_16x16x32_bf16 v[10:13], v[176:179], v[82:85], v[22:25]
	v_mfma_f32_16x16x32_bf16 v[82:85], v[184:187], v[188:191], v[10:13]
	v_mfma_f32_16x16x32_bf16 v[10:13], v[54:57], v[192:195], v[70:73]
	v_mfma_f32_16x16x32_bf16 v[70:73], v[172:175], v[196:199], v[10:13]
	v_mfma_f32_16x16x32_bf16 v[10:13], v[176:179], v[192:195], v[66:69]
	v_mfma_f32_16x16x32_bf16 v[66:69], v[184:187], v[196:199], v[10:13]
	v_mfma_f32_16x16x32_bf16 v[10:13], v[54:57], v[200:203], v[46:49]
	v_mfma_f32_16x16x32_bf16 v[46:49], v[172:175], v[204:207], v[10:13]
	v_mfma_f32_16x16x32_bf16 v[10:13], v[176:179], v[200:203], v[42:45]
	v_mfma_f32_16x16x32_bf16 v[6:9], v[54:57], v[208:211], v[6:9]
	v_mfma_f32_16x16x32_bf16 v[2:5], v[176:179], v[208:211], v[2:5]
	v_mfma_f32_16x16x32_bf16 v[42:45], v[184:187], v[204:207], v[10:13]
	v_mfma_f32_16x16x32_bf16 v[6:9], v[172:175], v[216:219], v[6:9]
	v_mfma_f32_16x16x32_bf16 v[2:5], v[184:187], v[216:219], v[2:5]
	s_setprio 0
	s_barrier
	s_add_i32 vcc_lo, vcc_lo, 2
	s_add_u32 s6, s6, 0x10000
	s_addc_u32 s7, s7, 0
	s_add_u32 s56, s56, 0x10000
	s_addc_u32 s57, s57, 0
	s_cmp_gt_u32 vcc_lo, 29
	s_cbranch_scc0 .LBB0_328
	s_and_b64 vcc, exec, s[26:27]
	s_cbranch_vccz .LBB0_331
	s_barrier

; #define PG8_STAGE(bufoff, gbase, voff) do { _Pragma("unroll") for (int _i = 0; _i < 2; ++_i) \
;         __builtin_amdgcn_global_load_lds((const unsigned*)((const char*)(gbase) + (voff)[_i]), (PG8_LAS unsigned*)(lds + (bufoff) + ldsw + _i * 8192), 16, 0, 0); } while (0)
; #define PG8_LDA(dst, b, h) do { _Pragma("unroll") for (int m = 0; m < 4; ++m) _Pragma("unroll") for (int k = 0; k < 2; ++k) dst[m][k] = *(const PG8_LAS bf16x8*)(lds + PG8_SA(b, h) + aoff + m * 2048 + k * 1024); } while (0)
; #define PG8_LDB(dst, b, h) do { _Pragma("unroll") for (int n = 0; n < 2; ++n) _Pragma("unroll") for (int k = 0; k < 2; ++k) dst[n][k] = *(const PG8_LAS bf16x8*)(lds + PG8_SB(b, h) + boff + n * 2048 + k * 1024); } while (0)
; #define PG8_MMA(ai, bj, At, Bt) do { __builtin_amdgcn_s_setprio(1); _Pragma("unroll") for (int m = 0; m < 4; ++m) _Pragma("unroll") for (int n = 0; n < 2; ++n) _Pragma("unroll") for (int k = 0; k < 2; ++k) \
;         acc[ai][bj][m][n] = __builtin_amdgcn_mfma_f32_16x16x32_bf16(Bt[n][k], At[m][k], acc[ai][bj][m][n], 0, 0, 0); __builtin_amdgcn_s_setprio(0); } while (0)
; #define PG8_WAIT_V(n) asm volatile("s_waitcnt vmcnt(" #n ")" ::: "memory")
; #define PG8_WAIT_L(n) asm volatile("s_waitcnt lgkmcnt(" #n ")" ::: "memory")
; #define PG8_BAR __builtin_amdgcn_s_barrier()
; #define PG8_SCHED __builtin_amdgcn_sched_barrier(0)
;     ...
;         for (int t = 0; t < nt; t += 2) {
;             const bool last = (t == nt - 2);
;             const char* a1 = cA + (ptrdiff_t)(t + 1) * kstepA;
;             const char* a2 = last ? nA : cA + (ptrdiff_t)(t + 2) * kstepA; const char* b2 = last ? nB : cB + (ptrdiff_t)(t + 2) * kstep;
;             const char* a3 = a2 + kstepA; const char* b3 = b2 + kstep;
;             if (last && has_next) S.a_ready(nxt);
;             if constexpr (SP2) {
;             PG8_LDB(B0, 0, 0); PG8_LDB(B1, 0, 1); PG8_SCHED; PG8_LDA(At, 0, 0); PG8_STAGE(PG8_SA(1, 1), a1 + hstepA, voffA);
;             PG8_WAIT_V(8); PG8_WAIT_L(0); PG8_BAR; PG8_MMA(0, 0, At, B0); PG8_MMA(0, 1, At, B1); PG8_BAR; PG8_SCHED;
;             PG8_LDA(At, 0, 1); PG8_STAGE(PG8_SB(0, 0), b2, voffB); PG8_STAGE(PG8_SB(0, 1), b2 + hstepB, voffB); PG8_STAGE(PG8_SA(0, 0), a2, voffA);
;             PG8_WAIT_V(8); PG8_WAIT_L(0); PG8_BAR; PG8_MMA(1, 0, At, B0); PG8_MMA(1, 1, At, B1); PG8_BAR; PG8_SCHED;
.LBB0_1128:
	s_add_u32 s36, s34, 0x4000
	s_addc_u32 s37, s35, 0
	s_cmp_eq_u32 s57, 28
	s_cselect_b32 s86, s29, s36
	s_cselect_b32 s87, s23, s37
	s_cselect_b32 s46, s31, s44
	s_cselect_b32 s47, s21, s56
	s_add_u32 s36, s86, 0x8000
	s_addc_u32 s37, s87, 0
	s_add_i32 s65, 0, 0x10000
	v_add_u32_e32 v0, s65, v242
	s_add_i32 s66, 0, 0x14000
	s_waitcnt lgkmcnt(0)
	ds_read_b128 v[130:133], v0
	ds_read_b128 v[134:137], v0 offset:1024
	ds_read_b128 v[138:141], v0 offset:2048
	ds_read_b128 v[142:145], v0 offset:3072
	v_add_u32_e32 v0, s66, v242
	ds_read_b128 v[146:149], v0
	ds_read_b128 v[150:153], v0 offset:1024
	ds_read_b128 v[154:157], v0 offset:2048
	ds_read_b128 v[158:161], v0 offset:3072
	s_add_i32 m0, s51, 0xc000
	ds_read_b128 v[162:165], v243
	ds_read_b128 v[166:169], v243 offset:1024
	ds_read_b128 v[170:173], v243 offset:2048
	ds_read_b128 v[174:177], v243 offset:3072
	ds_read_b128 v[178:181], v243 offset:4096
	ds_read_b128 v[182:185], v243 offset:5120
	ds_read_b128 v[198:201], v243 offset:6144
	ds_read_b128 v[202:205], v243 offset:7168
	global_load_lds_dwordx4 v194, s[34:35]
	s_add_i32 m0, s51, 0xe000
	s_nop 0
	global_load_lds_dwordx4 v196, s[34:35]
	s_waitcnt vmcnt(8)
	s_waitcnt lgkmcnt(0)
	s_barrier
	s_setprio 1
	s_waitcnt lgkmcnt(0)
	v_mfma_f32_16x16x32_bf16 v[126:129], v[130:133], v[162:165], v[126:129]
	v_mfma_f32_16x16x32_bf16 v[126:129], v[134:137], v[166:169], v[126:129]
	v_mfma_f32_16x16x32_bf16 v[122:125], v[138:141], v[162:165], v[122:125]
	v_mfma_f32_16x16x32_bf16 v[122:125], v[142:145], v[166:169], v[122:125]
	v_mfma_f32_16x16x32_bf16 v[110:113], v[130:133], v[170:173], v[110:113]
	v_mfma_f32_16x16x32_bf16 v[110:113], v[134:137], v[174:177], v[110:113]
	v_mfma_f32_16x16x32_bf16 v[106:109], v[138:141], v[170:173], v[106:109]
	v_mfma_f32_16x16x32_bf16 v[106:109], v[142:145], v[174:177], v[106:109]
	v_mfma_f32_16x16x32_bf16 v[94:97], v[130:133], v[178:181], v[94:97]
	v_mfma_f32_16x16x32_bf16 v[94:97], v[134:137], v[182:185], v[94:97]
	v_mfma_f32_16x16x32_bf16 v[90:93], v[138:141], v[178:181], v[90:93]
	v_mfma_f32_16x16x32_bf16 v[90:93], v[142:145], v[182:185], v[90:93]
	v_mfma_f32_16x16x32_bf16 v[78:81], v[130:133], v[198:201], v[78:81]
	v_mfma_f32_16x16x32_bf16 v[78:81], v[134:137], v[202:205], v[78:81]
	v_mfma_f32_16x16x32_bf16 v[74:77], v[138:141], v[198:201], v[74:77]
	v_mfma_f32_16x16x32_bf16 v[74:77], v[142:145], v[202:205], v[74:77]
	s_setprio 0
	s_setprio 1
	v_mfma_f32_16x16x32_bf16 v[118:121], v[146:149], v[162:165], v[118:121]
	v_mfma_f32_16x16x32_bf16 v[118:121], v[150:153], v[166:169], v[118:121]
	v_mfma_f32_16x16x32_bf16 v[114:117], v[154:157], v[162:165], v[114:117]
	v_mfma_f32_16x16x32_bf16 v[114:117], v[158:161], v[166:169], v[114:117]
	v_mfma_f32_16x16x32_bf16 v[102:105], v[146:149], v[170:173], v[102:105]
	v_mfma_f32_16x16x32_bf16 v[102:105], v[150:153], v[174:177], v[102:105]
	v_mfma_f32_16x16x32_bf16 v[98:101], v[154:157], v[170:173], v[98:101]
	v_mfma_f32_16x16x32_bf16 v[98:101], v[158:161], v[174:177], v[98:101]
	v_mfma_f32_16x16x32_bf16 v[86:89], v[146:149], v[178:181], v[86:89]
	v_mfma_f32_16x16x32_bf16 v[86:89], v[150:153], v[182:185], v[86:89]
	v_mfma_f32_16x16x32_bf16 v[82:85], v[154:157], v[178:181], v[82:85]
	v_mfma_f32_16x16x32_bf16 v[82:85], v[158:161], v[182:185], v[82:85]
	v_mfma_f32_16x16x32_bf16 v[70:73], v[146:149], v[198:201], v[70:73]
	v_mfma_f32_16x16x32_bf16 v[70:73], v[150:153], v[202:205], v[70:73]
	v_mfma_f32_16x16x32_bf16 v[66:69], v[154:157], v[198:201], v[66:69]
	v_mfma_f32_16x16x32_bf16 v[66:69], v[158:161], v[202:205], v[66:69]
	s_setprio 0
	s_barrier
	s_add_i32 s65, s65, s49
	s_mov_b32 m0, s65
	ds_read_b128 v[162:165], v243 offset:16384
	ds_read_b128 v[166:169], v243 offset:17408
	ds_read_b128 v[170:173], v243 offset:18432
	ds_read_b128 v[174:177], v243 offset:19456
	ds_read_b128 v[178:181], v243 offset:20480
	ds_read_b128 v[182:185], v243 offset:21504
	ds_read_b128 v[198:201], v243 offset:22528
	ds_read_b128 v[202:205], v243 offset:23552
	global_load_lds_dwordx4 v188, s[46:47]
	s_add_i32 m0, s65, 0x2000
	s_add_u32 s90, s46, 0x4000
	s_addc_u32 s91, s47, 0
	s_add_i32 s65, s66, s49
	global_load_lds_dwordx4 v192, s[46:47]
	s_mov_b32 m0, s65
	s_nop 0
	global_load_lds_dwordx4 v188, s[90:91]
	s_add_i32 m0, s65, 0x2000
	s_nop 0
	global_load_lds_dwordx4 v192, s[90:91]
	s_mov_b32 m0, s51
	s_nop 0
	global_load_lds_dwordx4 v186, s[86:87]
	s_mov_b32 m0, s54
	s_nop 0
	global_load_lds_dwordx4 v190, s[86:87]
	s_waitcnt vmcnt(8)
	s_waitcnt lgkmcnt(0)
	s_barrier
	s_setprio 1
	s_waitcnt lgkmcnt(0)
	v_mfma_f32_16x16x32_bf16 v[62:65], v[130:133], v[162:165], v[62:65]
	v_mfma_f32_16x16x32_bf16 v[62:65], v[134:137], v[166:169], v[62:65]
	v_mfma_f32_16x16x32_bf16 v[58:61], v[138:141], v[162:165], v[58:61]
	v_mfma_f32_16x16x32_bf16 v[58:61], v[142:145], v[166:169], v[58:61]
	v_mfma_f32_16x16x32_bf16 v[46:49], v[130:133], v[170:173], v[46:49]
	v_mfma_f32_16x16x32_bf16 v[46:49], v[134:137], v[174:177], v[46:49]
	v_mfma_f32_16x16x32_bf16 v[42:45], v[138:141], v[170:173], v[42:45]
	v_mfma_f32_16x16x32_bf16 v[42:45], v[142:145], v[174:177], v[42:45]
	v_mfma_f32_16x16x32_bf16 v[30:33], v[130:133], v[178:181], v[30:33]
	v_mfma_f32_16x16x32_bf16 v[30:33], v[134:137], v[182:185], v[30:33]
	v_mfma_f32_16x16x32_bf16 v[26:29], v[138:141], v[178:181], v[26:29]
	v_mfma_f32_16x16x32_bf16 v[26:29], v[142:145], v[182:185], v[26:29]
	v_mfma_f32_16x16x32_bf16 v[14:17], v[130:133], v[198:201], v[14:17]
	v_mfma_f32_16x16x32_bf16 v[14:17], v[134:137], v[202:205], v[14:17]
	v_mfma_f32_16x16x32_bf16 v[10:13], v[138:141], v[198:201], v[10:13]
	v_mfma_f32_16x16x32_bf16 v[10:13], v[142:145], v[202:205], v[10:13]
	s_setprio 0
	s_setprio 1
	v_mfma_f32_16x16x32_bf16 v[54:57], v[146:149], v[162:165], v[54:57]
	v_mfma_f32_16x16x32_bf16 v[54:57], v[150:153], v[166:169], v[54:57]
	v_mfma_f32_16x16x32_bf16 v[50:53], v[154:157], v[162:165], v[50:53]
	v_mfma_f32_16x16x32_bf16 v[50:53], v[158:161], v[166:169], v[50:53]
	v_mfma_f32_16x16x32_bf16 v[38:41], v[146:149], v[170:173], v[38:41]
	v_mfma_f32_16x16x32_bf16 v[38:41], v[150:153], v[174:177], v[38:41]
	v_mfma_f32_16x16x32_bf16 v[34:37], v[154:157], v[170:173], v[34:37]
	v_mfma_f32_16x16x32_bf16 v[34:37], v[158:161], v[174:177], v[34:37]
	v_mfma_f32_16x16x32_bf16 v[22:25], v[146:149], v[178:181], v[22:25]
	v_mfma_f32_16x16x32_bf16 v[22:25], v[150:153], v[182:185], v[22:25]
	v_mfma_f32_16x16x32_bf16 v[18:21], v[154:157], v[178:181], v[18:21]
	v_mfma_f32_16x16x32_bf16 v[18:21], v[158:161], v[182:185], v[18:21]
	v_mfma_f32_16x16x32_bf16 v[6:9], v[146:149], v[198:201], v[6:9]
	v_mfma_f32_16x16x32_bf16 v[6:9], v[150:153], v[202:205], v[6:9]
	v_mfma_f32_16x16x32_bf16 v[2:5], v[154:157], v[198:201], v[2:5]
	v_mfma_f32_16x16x32_bf16 v[2:5], v[158:161], v[202:205], v[2:5]
	s_setprio 0
	s_barrier
; #define PG8_STAGE(bufoff, gbase, voff) do { _Pragma("unroll") for (int _i = 0; _i < 2; ++_i) \
;         __builtin_amdgcn_global_load_lds((const unsigned*)((const char*)(gbase) + (voff)[_i]), (PG8_LAS unsigned*)(lds + (bufoff) + ldsw + _i * 8192), 16, 0, 0); } while (0)
; #define PG8_LDA(dst, b, h) do { _Pragma("unroll") for (int m = 0; m < 4; ++m) _Pragma("unroll") for (int k = 0; k < 2; ++k) dst[m][k] = *(const PG8_LAS bf16x8*)(lds + PG8_SA(b, h) + aoff + m * 2048 + k * 1024); } while (0)
; #define PG8_LDB(dst, b, h) do { _Pragma("unroll") for (int n = 0; n < 2; ++n) _Pragma("unroll") for (int k = 0; k < 2; ++k) dst[n][k] = *(const PG8_LAS bf16x8*)(lds + PG8_SB(b, h) + boff + n * 2048 + k * 1024); } while (0)
; #define PG8_MMA(ai, bj, At, Bt) do { __builtin_amdgcn_s_setprio(1); _Pragma("unroll") for (int m = 0; m < 4; ++m) _Pragma("unroll") for (int n = 0; n < 2; ++n) _Pragma("unroll") for (int k = 0; k < 2; ++k) \
;         acc[ai][bj][m][n] = __builtin_amdgcn_mfma_f32_16x16x32_bf16(Bt[n][k], At[m][k], acc[ai][bj][m][n], 0, 0, 0); __builtin_amdgcn_s_setprio(0); } while (0)
; #define PG8_WAIT_V(n) asm volatile("s_waitcnt vmcnt(" #n ")" ::: "memory")
; #define PG8_WAIT_L(n) asm volatile("s_waitcnt lgkmcnt(" #n ")" ::: "memory")
; #define PG8_BAR __builtin_amdgcn_s_barrier()
; #define PG8_SCHED __builtin_amdgcn_sched_barrier(0)
;     ...
;             PG8_LDB(B0, 1, 0); PG8_LDB(B1, 1, 1); PG8_SCHED; PG8_LDA(At, 1, 0); PG8_STAGE(PG8_SA(0, 1), a2 + hstepA, voffA);
;             PG8_WAIT_V(8); PG8_WAIT_L(0); PG8_BAR; PG8_MMA(0, 0, At, B0); PG8_MMA(0, 1, At, B1); PG8_BAR; PG8_SCHED;
;             PG8_LDA(At, 1, 1); PG8_STAGE(PG8_SB(1, 0), b3, voffB); PG8_STAGE(PG8_SB(1, 1), b3 + hstepB, voffB); PG8_STAGE(PG8_SA(1, 0), a3, voffA);
;             PG8_WAIT_V(8); PG8_WAIT_L(0); PG8_BAR; PG8_MMA(1, 0, At, B0); PG8_MMA(1, 1, At, B1); PG8_BAR; PG8_SCHED;
	s_add_i32 s65, 0, 0x18000
	v_add_u32_e32 v0, s65, v242
	s_add_i32 s66, 0, 0x1c000
	ds_read_b128 v[130:133], v0
	ds_read_b128 v[134:137], v0 offset:1024
	ds_read_b128 v[138:141], v0 offset:2048
	ds_read_b128 v[142:145], v0 offset:3072
	v_add_u32_e32 v0, s66, v242
	ds_read_b128 v[146:149], v0
	ds_read_b128 v[150:153], v0 offset:1024
	ds_read_b128 v[154:157], v0 offset:2048
	ds_read_b128 v[158:161], v0 offset:3072
	s_add_u32 s86, s86, 0x4000
	s_addc_u32 s87, s87, 0
	s_mov_b32 m0, s55
	ds_read_b128 v[162:165], v243 offset:32768
	ds_read_b128 v[166:169], v243 offset:33792
	ds_read_b128 v[170:173], v243 offset:34816
	ds_read_b128 v[174:177], v243 offset:35840
	ds_read_b128 v[178:181], v243 offset:36864
	ds_read_b128 v[182:185], v243 offset:37888
	ds_read_b128 v[198:201], v243 offset:38912
	ds_read_b128 v[202:205], v243 offset:39936
	global_load_lds_dwordx4 v186, s[86:87]
	s_mov_b32 m0, s61
	s_nop 0
	global_load_lds_dwordx4 v190, s[86:87]
	s_waitcnt vmcnt(8)
	s_waitcnt lgkmcnt(0)
	s_barrier
	s_setprio 1
	s_waitcnt lgkmcnt(0)
	v_mfma_f32_16x16x32_bf16 v[126:129], v[130:133], v[162:165], v[126:129]
	v_mfma_f32_16x16x32_bf16 v[126:129], v[134:137], v[166:169], v[126:129]
	v_mfma_f32_16x16x32_bf16 v[122:125], v[138:141], v[162:165], v[122:125]
	v_mfma_f32_16x16x32_bf16 v[122:125], v[142:145], v[166:169], v[122:125]
	v_mfma_f32_16x16x32_bf16 v[110:113], v[130:133], v[170:173], v[110:113]
	v_mfma_f32_16x16x32_bf16 v[110:113], v[134:137], v[174:177], v[110:113]
	v_mfma_f32_16x16x32_bf16 v[106:109], v[138:141], v[170:173], v[106:109]
	v_mfma_f32_16x16x32_bf16 v[106:109], v[142:145], v[174:177], v[106:109]
	v_mfma_f32_16x16x32_bf16 v[94:97], v[130:133], v[178:181], v[94:97]
	v_mfma_f32_16x16x32_bf16 v[94:97], v[134:137], v[182:185], v[94:97]
	v_mfma_f32_16x16x32_bf16 v[90:93], v[138:141], v[178:181], v[90:93]
	v_mfma_f32_16x16x32_bf16 v[90:93], v[142:145], v[182:185], v[90:93]
	v_mfma_f32_16x16x32_bf16 v[78:81], v[130:133], v[198:201], v[78:81]
	v_mfma_f32_16x16x32_bf16 v[78:81], v[134:137], v[202:205], v[78:81]
	v_mfma_f32_16x16x32_bf16 v[74:77], v[138:141], v[198:201], v[74:77]
	v_mfma_f32_16x16x32_bf16 v[74:77], v[142:145], v[202:205], v[74:77]
	s_setprio 0
	s_setprio 1
	v_mfma_f32_16x16x32_bf16 v[118:121], v[146:149], v[162:165], v[118:121]
	v_mfma_f32_16x16x32_bf16 v[118:121], v[150:153], v[166:169], v[118:121]
	v_mfma_f32_16x16x32_bf16 v[114:117], v[154:157], v[162:165], v[114:117]
	v_mfma_f32_16x16x32_bf16 v[114:117], v[158:161], v[166:169], v[114:117]
	v_mfma_f32_16x16x32_bf16 v[102:105], v[146:149], v[170:173], v[102:105]
	v_mfma_f32_16x16x32_bf16 v[102:105], v[150:153], v[174:177], v[102:105]
	v_mfma_f32_16x16x32_bf16 v[98:101], v[154:157], v[170:173], v[98:101]
	v_mfma_f32_16x16x32_bf16 v[98:101], v[158:161], v[174:177], v[98:101]
	v_mfma_f32_16x16x32_bf16 v[86:89], v[146:149], v[178:181], v[86:89]
	v_mfma_f32_16x16x32_bf16 v[86:89], v[150:153], v[182:185], v[86:89]
	v_mfma_f32_16x16x32_bf16 v[82:85], v[154:157], v[178:181], v[82:85]
	v_mfma_f32_16x16x32_bf16 v[82:85], v[158:161], v[182:185], v[82:85]
	v_mfma_f32_16x16x32_bf16 v[70:73], v[146:149], v[198:201], v[70:73]
	v_mfma_f32_16x16x32_bf16 v[70:73], v[150:153], v[202:205], v[70:73]
	v_mfma_f32_16x16x32_bf16 v[66:69], v[154:157], v[198:201], v[66:69]
	v_mfma_f32_16x16x32_bf16 v[66:69], v[158:161], v[202:205], v[66:69]
	s_setprio 0
	s_barrier
	s_add_u32 s86, s46, 0x8000
	s_addc_u32 s87, s47, 0
	s_add_i32 s65, s65, s49
	s_mov_b32 m0, s65
	ds_read_b128 v[162:165], v243 offset:49152
	ds_read_b128 v[166:169], v243 offset:50176
	ds_read_b128 v[170:173], v243 offset:51200
	ds_read_b128 v[174:177], v243 offset:52224
	ds_read_b128 v[178:181], v243 offset:53248
	ds_read_b128 v[182:185], v243 offset:54272
	ds_read_b128 v[198:201], v243 offset:55296
	ds_read_b128 v[202:205], v243 offset:56320
	global_load_lds_dwordx4 v188, s[86:87]
	s_add_i32 m0, s65, 0x2000
	s_add_u32 s46, s46, 0xc000
	s_addc_u32 s47, s47, 0
	s_add_i32 s65, s66, s49
	global_load_lds_dwordx4 v192, s[86:87]
	s_mov_b32 m0, s65
	s_nop 0
	global_load_lds_dwordx4 v188, s[46:47]
	s_add_i32 m0, s65, 0x2000
	s_nop 0
	global_load_lds_dwordx4 v192, s[46:47]
	s_mov_b32 m0, s83
	s_nop 0
	global_load_lds_dwordx4 v186, s[36:37]
	v_lshl_add_u64 v[206:207], s[36:37], 0, v[190:191]
	s_mov_b32 m0, s85
	s_nop 0
	global_load_lds_dwordx4 v[206:207], off
	s_waitcnt vmcnt(8)
	s_waitcnt lgkmcnt(0)
	s_barrier
	s_setprio 1
	s_waitcnt lgkmcnt(0)
	v_mfma_f32_16x16x32_bf16 v[62:65], v[130:133], v[162:165], v[62:65]
	v_mfma_f32_16x16x32_bf16 v[62:65], v[134:137], v[166:169], v[62:65]
	v_mfma_f32_16x16x32_bf16 v[58:61], v[138:141], v[162:165], v[58:61]
	v_mfma_f32_16x16x32_bf16 v[58:61], v[142:145], v[166:169], v[58:61]
	v_mfma_f32_16x16x32_bf16 v[46:49], v[130:133], v[170:173], v[46:49]
	v_mfma_f32_16x16x32_bf16 v[46:49], v[134:137], v[174:177], v[46:49]
	v_mfma_f32_16x16x32_bf16 v[42:45], v[138:141], v[170:173], v[42:45]
	v_mfma_f32_16x16x32_bf16 v[42:45], v[142:145], v[174:177], v[42:45]
	v_mfma_f32_16x16x32_bf16 v[30:33], v[130:133], v[178:181], v[30:33]
	v_mfma_f32_16x16x32_bf16 v[30:33], v[134:137], v[182:185], v[30:33]
	v_mfma_f32_16x16x32_bf16 v[26:29], v[138:141], v[178:181], v[26:29]
	v_mfma_f32_16x16x32_bf16 v[26:29], v[142:145], v[182:185], v[26:29]
	v_mfma_f32_16x16x32_bf16 v[14:17], v[130:133], v[198:201], v[14:17]
	v_mfma_f32_16x16x32_bf16 v[14:17], v[134:137], v[202:205], v[14:17]
	v_mfma_f32_16x16x32_bf16 v[10:13], v[138:141], v[198:201], v[10:13]
	v_mfma_f32_16x16x32_bf16 v[10:13], v[142:145], v[202:205], v[10:13]
	s_setprio 0
	s_setprio 1
	v_mfma_f32_16x16x32_bf16 v[54:57], v[146:149], v[162:165], v[54:57]
	v_mfma_f32_16x16x32_bf16 v[54:57], v[150:153], v[166:169], v[54:57]
	v_mfma_f32_16x16x32_bf16 v[50:53], v[154:157], v[162:165], v[50:53]
	v_mfma_f32_16x16x32_bf16 v[50:53], v[158:161], v[166:169], v[50:53]
	v_mfma_f32_16x16x32_bf16 v[38:41], v[146:149], v[170:173], v[38:41]
	v_mfma_f32_16x16x32_bf16 v[38:41], v[150:153], v[174:177], v[38:41]
	v_mfma_f32_16x16x32_bf16 v[34:37], v[154:157], v[170:173], v[34:37]
	v_mfma_f32_16x16x32_bf16 v[34:37], v[158:161], v[174:177], v[34:37]
	v_mfma_f32_16x16x32_bf16 v[22:25], v[146:149], v[178:181], v[22:25]
	v_mfma_f32_16x16x32_bf16 v[22:25], v[150:153], v[182:185], v[22:25]
	v_mfma_f32_16x16x32_bf16 v[18:21], v[154:157], v[178:181], v[18:21]
	v_mfma_f32_16x16x32_bf16 v[18:21], v[158:161], v[182:185], v[18:21]
	v_mfma_f32_16x16x32_bf16 v[6:9], v[146:149], v[198:201], v[6:9]
	v_mfma_f32_16x16x32_bf16 v[6:9], v[150:153], v[202:205], v[6:9]
	v_mfma_f32_16x16x32_bf16 v[2:5], v[154:157], v[198:201], v[2:5]
	v_mfma_f32_16x16x32_bf16 v[2:5], v[158:161], v[202:205], v[2:5]
	s_setprio 0
	s_barrier
	s_add_i32 s57, s57, 2
	s_add_u32 s34, s34, 0x10000
	s_addc_u32 s35, s35, 0
	s_add_u32 s44, s44, 0x10000
	s_addc_u32 s56, s56, 0
	s_cmp_gt_u32 s57, 29
	s_cbranch_scc0 .LBB0_1128
	s_and_b64 vcc, exec, s[92:93]
	s_cbranch_vccz .LBB0_1131
	s_barrier

; #define PG8_STAGE(bufoff, gbase, voff) do { _Pragma("unroll") for (int _i = 0; _i < 2; ++_i) \
;         __builtin_amdgcn_global_load_lds((const unsigned*)((const char*)(gbase) + (voff)[_i]), (PG8_LAS unsigned*)(lds + (bufoff) + ldsw + _i * 8192), 16, 0, 0); } while (0)
; #define PG8_LDA(dst, b, h) do { _Pragma("unroll") for (int m = 0; m < 4; ++m) _Pragma("unroll") for (int k = 0; k < 2; ++k) dst[m][k] = *(const PG8_LAS bf16x8*)(lds + PG8_SA(b, h) + aoff + m * 2048 + k * 1024); } while (0)
; #define PG8_LDB(dst, b, h) do { _Pragma("unroll") for (int n = 0; n < 2; ++n) _Pragma("unroll") for (int k = 0; k < 2; ++k) dst[n][k] = *(const PG8_LAS bf16x8*)(lds + PG8_SB(b, h) + boff + n * 2048 + k * 1024); } while (0)
; #define PG8_MMA(ai, bj, At, Bt) do { __builtin_amdgcn_s_setprio(1); _Pragma("unroll") for (int m = 0; m < 4; ++m) _Pragma("unroll") for (int n = 0; n < 2; ++n) _Pragma("unroll") for (int k = 0; k < 2; ++k) \
;         acc[ai][bj][m][n] = __builtin_amdgcn_mfma_f32_16x16x32_bf16(Bt[n][k], At[m][k], acc[ai][bj][m][n], 0, 0, 0); __builtin_amdgcn_s_setprio(0); } while (0)
; #define PG8_WAIT_V(n) asm volatile("s_waitcnt vmcnt(" #n ")" ::: "memory")
; #define PG8_WAIT_L(n) asm volatile("s_waitcnt lgkmcnt(" #n ")" ::: "memory")
; #define PG8_BAR __builtin_amdgcn_s_barrier()
; #define PG8_SCHED __builtin_amdgcn_sched_barrier(0)
;     ...
;         for (int t = 0; t < nt; t += 2) {
;             const bool last = (t == nt - 2);
;             const char* a1 = cA + (ptrdiff_t)(t + 1) * kstepA;
;             const char* a2 = last ? nA : cA + (ptrdiff_t)(t + 2) * kstepA; const char* b2 = last ? nB : cB + (ptrdiff_t)(t + 2) * kstep;
;             const char* a3 = a2 + kstepA; const char* b3 = b2 + kstep;
;             if (last && has_next) S.a_ready(nxt);
;             if constexpr (SP2) {
;             PG8_LDB(B0, 0, 0); PG8_LDB(B1, 0, 1); PG8_SCHED; PG8_LDA(At, 0, 0); PG8_STAGE(PG8_SA(1, 1), a1 + hstepA, voffA);
;             PG8_WAIT_V(8); PG8_WAIT_L(0); PG8_BAR; PG8_MMA(0, 0, At, B0); PG8_MMA(0, 1, At, B1); PG8_BAR; PG8_SCHED;
;             PG8_LDA(At, 0, 1); PG8_STAGE(PG8_SB(0, 0), b2, voffB); PG8_STAGE(PG8_SB(0, 1), b2 + hstepB, voffB); PG8_STAGE(PG8_SA(0, 0), a2, voffA);
;             PG8_WAIT_V(8); PG8_WAIT_L(0); PG8_BAR; PG8_MMA(1, 0, At, B0); PG8_MMA(1, 1, At, B1); PG8_BAR; PG8_SCHED;
.LBB0_1256:
	s_add_u32 s36, s34, 0x10000
	s_addc_u32 s37, s35, 0
	s_cmp_eq_u32 s66, 28
	s_cselect_b32 s88, s57, s36
	s_cselect_b32 s89, s27, s37
	s_cselect_b32 s86, vcc_lo, vcc_hi
	s_cselect_b32 s87, s25, s65
	s_add_u32 s46, s88, 0x8000
	s_addc_u32 s47, s89, 0
	s_add_i32 s96, 0, 0x10000
	v_add_u32_e32 v0, s96, v192
	s_add_i32 s97, 0, 0x14000
	ds_read_b128 v[130:133], v0
	ds_read_b128 v[134:137], v0 offset:1024
	ds_read_b128 v[138:141], v0 offset:2048
	ds_read_b128 v[142:145], v0 offset:3072
	v_add_u32_e32 v0, s97, v192
	ds_read_b128 v[146:149], v0
	ds_read_b128 v[150:153], v0 offset:1024
	ds_read_b128 v[154:157], v0 offset:2048
	ds_read_b128 v[170:173], v0 offset:3072
	s_add_i32 m0, s48, 0xc000
	ds_read_b128 v[174:177], v193
	ds_read_b128 v[178:181], v193 offset:1024
	ds_read_b128 v[182:185], v193 offset:2048
	ds_read_b128 v[186:189], v193 offset:3072
	ds_read_b128 v[194:197], v193 offset:4096
	ds_read_b128 v[198:201], v193 offset:5120
	ds_read_b128 v[202:205], v193 offset:6144
	ds_read_b128 v[206:209], v193 offset:7168
	global_load_lds_dwordx4 v166, s[34:35]
	s_add_i32 m0, s48, 0xe000
	s_nop 0
	global_load_lds_dwordx4 v168, s[34:35]
	s_waitcnt vmcnt(8)
	s_waitcnt lgkmcnt(0)
	s_barrier
	s_setprio 1
	s_waitcnt lgkmcnt(0)
	v_mfma_f32_16x16x32_bf16 v[126:129], v[130:133], v[174:177], v[126:129]
	v_mfma_f32_16x16x32_bf16 v[126:129], v[134:137], v[178:181], v[126:129]
	v_mfma_f32_16x16x32_bf16 v[122:125], v[138:141], v[174:177], v[122:125]
	v_mfma_f32_16x16x32_bf16 v[122:125], v[142:145], v[178:181], v[122:125]
	v_mfma_f32_16x16x32_bf16 v[118:121], v[130:133], v[182:185], v[118:121]
	v_mfma_f32_16x16x32_bf16 v[118:121], v[134:137], v[186:189], v[118:121]
	v_mfma_f32_16x16x32_bf16 v[114:117], v[138:141], v[182:185], v[114:117]
	v_mfma_f32_16x16x32_bf16 v[114:117], v[142:145], v[186:189], v[114:117]
	v_mfma_f32_16x16x32_bf16 v[110:113], v[130:133], v[194:197], v[110:113]
	v_mfma_f32_16x16x32_bf16 v[110:113], v[134:137], v[198:201], v[110:113]
	v_mfma_f32_16x16x32_bf16 v[106:109], v[138:141], v[194:197], v[106:109]
	v_mfma_f32_16x16x32_bf16 v[106:109], v[142:145], v[198:201], v[106:109]
	v_mfma_f32_16x16x32_bf16 v[102:105], v[130:133], v[202:205], v[102:105]
	v_mfma_f32_16x16x32_bf16 v[102:105], v[134:137], v[206:209], v[102:105]
	v_mfma_f32_16x16x32_bf16 v[98:101], v[138:141], v[202:205], v[98:101]
	v_mfma_f32_16x16x32_bf16 v[98:101], v[142:145], v[206:209], v[98:101]
	s_setprio 0
	s_setprio 1
	v_mfma_f32_16x16x32_bf16 v[30:33], v[146:149], v[174:177], v[30:33]
	v_mfma_f32_16x16x32_bf16 v[30:33], v[150:153], v[178:181], v[30:33]
	v_mfma_f32_16x16x32_bf16 v[46:49], v[154:157], v[174:177], v[46:49]
	v_mfma_f32_16x16x32_bf16 v[46:49], v[170:173], v[178:181], v[46:49]
	v_mfma_f32_16x16x32_bf16 v[26:29], v[146:149], v[182:185], v[26:29]
	v_mfma_f32_16x16x32_bf16 v[26:29], v[150:153], v[186:189], v[26:29]
	v_mfma_f32_16x16x32_bf16 v[34:37], v[154:157], v[182:185], v[34:37]
	v_mfma_f32_16x16x32_bf16 v[34:37], v[170:173], v[186:189], v[34:37]
	v_mfma_f32_16x16x32_bf16 v[94:97], v[146:149], v[194:197], v[94:97]
	v_mfma_f32_16x16x32_bf16 v[94:97], v[150:153], v[198:201], v[94:97]
	v_mfma_f32_16x16x32_bf16 v[90:93], v[154:157], v[194:197], v[90:93]
	v_mfma_f32_16x16x32_bf16 v[90:93], v[170:173], v[198:201], v[90:93]
	v_mfma_f32_16x16x32_bf16 v[86:89], v[146:149], v[202:205], v[86:89]
	v_mfma_f32_16x16x32_bf16 v[86:89], v[150:153], v[206:209], v[86:89]
	v_mfma_f32_16x16x32_bf16 v[82:85], v[154:157], v[202:205], v[82:85]
	v_mfma_f32_16x16x32_bf16 v[82:85], v[170:173], v[206:209], v[82:85]
	s_setprio 0
	s_barrier
	s_add_i32 s34, s96, s44
	s_mov_b32 m0, s34
	ds_read_b128 v[174:177], v193 offset:16384
	ds_read_b128 v[178:181], v193 offset:17408
	ds_read_b128 v[182:185], v193 offset:18432
	ds_read_b128 v[186:189], v193 offset:19456
	ds_read_b128 v[194:197], v193 offset:20480
	ds_read_b128 v[198:201], v193 offset:21504
	ds_read_b128 v[202:205], v193 offset:22528
	ds_read_b128 v[206:209], v193 offset:23552
	global_load_lds_dwordx4 v162, s[86:87]
	s_add_i32 m0, s34, 0x2000
	s_add_u32 s34, s86, 0x4000
	s_addc_u32 s35, s87, 0
	s_add_i32 s96, s97, s44
	global_load_lds_dwordx4 v158, s[86:87]
	s_mov_b32 m0, s96
	v_lshl_add_u64 v[210:211], s[88:89], 0, v[160:161]
	global_load_lds_dwordx4 v162, s[34:35]
	s_add_i32 m0, s96, 0x2000
	s_nop 0
	global_load_lds_dwordx4 v158, s[34:35]
	v_lshl_add_u64 v[190:191], s[88:89], 0, v[164:165]
	s_mov_b32 m0, s48
	s_nop 0
	global_load_lds_dwordx4 v[190:191], off
	s_mov_b32 m0, s49
	s_nop 0
	global_load_lds_dwordx4 v[210:211], off
	s_waitcnt vmcnt(8)
	s_waitcnt lgkmcnt(0)
	s_barrier
; #define PG8_STAGE(bufoff, gbase, voff) do { _Pragma("unroll") for (int _i = 0; _i < 2; ++_i) \
;         __builtin_amdgcn_global_load_lds((const unsigned*)((const char*)(gbase) + (voff)[_i]), (PG8_LAS unsigned*)(lds + (bufoff) + ldsw + _i * 8192), 16, 0, 0); } while (0)
; #define PG8_LDA(dst, b, h) do { _Pragma("unroll") for (int m = 0; m < 4; ++m) _Pragma("unroll") for (int k = 0; k < 2; ++k) dst[m][k] = *(const PG8_LAS bf16x8*)(lds + PG8_SA(b, h) + aoff + m * 2048 + k * 1024); } while (0)
; #define PG8_LDB(dst, b, h) do { _Pragma("unroll") for (int n = 0; n < 2; ++n) _Pragma("unroll") for (int k = 0; k < 2; ++k) dst[n][k] = *(const PG8_LAS bf16x8*)(lds + PG8_SB(b, h) + boff + n * 2048 + k * 1024); } while (0)
; #define PG8_MMA(ai, bj, At, Bt) do { __builtin_amdgcn_s_setprio(1); _Pragma("unroll") for (int m = 0; m < 4; ++m) _Pragma("unroll") for (int n = 0; n < 2; ++n) _Pragma("unroll") for (int k = 0; k < 2; ++k) \
;         acc[ai][bj][m][n] = __builtin_amdgcn_mfma_f32_16x16x32_bf16(Bt[n][k], At[m][k], acc[ai][bj][m][n], 0, 0, 0); __builtin_amdgcn_s_setprio(0); } while (0)
; #define PG8_WAIT_V(n) asm volatile("s_waitcnt vmcnt(" #n ")" ::: "memory")
; #define PG8_WAIT_L(n) asm volatile("s_waitcnt lgkmcnt(" #n ")" ::: "memory")
; #define PG8_BAR __builtin_amdgcn_s_barrier()
; #define PG8_SCHED __builtin_amdgcn_sched_barrier(0)
;     ...
;             PG8_WAIT_V(8); PG8_WAIT_L(0); PG8_BAR; PG8_MMA(1, 0, At, B0); PG8_MMA(1, 1, At, B1); PG8_BAR; PG8_SCHED;
;             PG8_LDB(B0, 1, 0); PG8_LDB(B1, 1, 1); PG8_SCHED; PG8_LDA(At, 1, 0); PG8_STAGE(PG8_SA(0, 1), a2 + hstepA, voffA);
;             PG8_WAIT_V(8); PG8_WAIT_L(0); PG8_BAR; PG8_MMA(0, 0, At, B0); PG8_MMA(0, 1, At, B1); PG8_BAR; PG8_SCHED;
	s_setprio 1
	s_waitcnt lgkmcnt(0)
	v_mfma_f32_16x16x32_bf16 v[78:81], v[130:133], v[174:177], v[78:81]
	v_mfma_f32_16x16x32_bf16 v[78:81], v[134:137], v[178:181], v[78:81]
	v_mfma_f32_16x16x32_bf16 v[74:77], v[138:141], v[174:177], v[74:77]
	v_mfma_f32_16x16x32_bf16 v[74:77], v[142:145], v[178:181], v[74:77]
	v_mfma_f32_16x16x32_bf16 v[70:73], v[130:133], v[182:185], v[70:73]
	v_mfma_f32_16x16x32_bf16 v[70:73], v[134:137], v[186:189], v[70:73]
	v_mfma_f32_16x16x32_bf16 v[66:69], v[138:141], v[182:185], v[66:69]
	v_mfma_f32_16x16x32_bf16 v[66:69], v[142:145], v[186:189], v[66:69]
	v_mfma_f32_16x16x32_bf16 v[42:45], v[130:133], v[194:197], v[42:45]
	v_mfma_f32_16x16x32_bf16 v[42:45], v[134:137], v[198:201], v[42:45]
	v_mfma_f32_16x16x32_bf16 v[6:9], v[138:141], v[194:197], v[6:9]
	v_mfma_f32_16x16x32_bf16 v[6:9], v[142:145], v[198:201], v[6:9]
	v_mfma_f32_16x16x32_bf16 v[38:41], v[130:133], v[202:205], v[38:41]
	v_mfma_f32_16x16x32_bf16 v[38:41], v[134:137], v[206:209], v[38:41]
	v_mfma_f32_16x16x32_bf16 v[2:5], v[138:141], v[202:205], v[2:5]
	v_mfma_f32_16x16x32_bf16 v[2:5], v[142:145], v[206:209], v[2:5]
	s_setprio 0
	s_setprio 1
	v_mfma_f32_16x16x32_bf16 v[62:65], v[146:149], v[174:177], v[62:65]
	v_mfma_f32_16x16x32_bf16 v[62:65], v[150:153], v[178:181], v[62:65]
	v_mfma_f32_16x16x32_bf16 v[58:61], v[154:157], v[174:177], v[58:61]
	v_mfma_f32_16x16x32_bf16 v[58:61], v[170:173], v[178:181], v[58:61]
	v_mfma_f32_16x16x32_bf16 v[54:57], v[146:149], v[182:185], v[54:57]
	v_mfma_f32_16x16x32_bf16 v[54:57], v[150:153], v[186:189], v[54:57]
	v_mfma_f32_16x16x32_bf16 v[50:53], v[154:157], v[182:185], v[50:53]
	v_mfma_f32_16x16x32_bf16 v[50:53], v[170:173], v[186:189], v[50:53]
	v_mfma_f32_16x16x32_bf16 v[22:25], v[146:149], v[194:197], v[22:25]
	v_mfma_f32_16x16x32_bf16 v[22:25], v[150:153], v[198:201], v[22:25]
	v_mfma_f32_16x16x32_bf16 v[18:21], v[154:157], v[194:197], v[18:21]
	v_mfma_f32_16x16x32_bf16 v[18:21], v[170:173], v[198:201], v[18:21]
	v_mfma_f32_16x16x32_bf16 v[14:17], v[146:149], v[202:205], v[14:17]
	v_mfma_f32_16x16x32_bf16 v[14:17], v[150:153], v[206:209], v[14:17]
	v_mfma_f32_16x16x32_bf16 v[10:13], v[154:157], v[202:205], v[10:13]
	v_mfma_f32_16x16x32_bf16 v[10:13], v[170:173], v[206:209], v[10:13]
	s_setprio 0
	s_barrier
	s_add_i32 s88, 0, 0x18000
	v_add_u32_e32 v0, s88, v192
	s_add_i32 s89, 0, 0x1c000
	ds_read_b128 v[130:133], v0
	ds_read_b128 v[134:137], v0 offset:1024
	ds_read_b128 v[138:141], v0 offset:2048
	ds_read_b128 v[142:145], v0 offset:3072
	v_add_u32_e32 v0, s89, v192
	ds_read_b128 v[146:149], v0
	ds_read_b128 v[150:153], v0 offset:1024
	ds_read_b128 v[154:157], v0 offset:2048
	ds_read_b128 v[170:173], v0 offset:3072
	s_mov_b32 m0, s51
	v_lshl_add_u64 v[190:191], v[190:191], 0, s[58:59]
	ds_read_b128 v[174:177], v193 offset:32768
	ds_read_b128 v[178:181], v193 offset:33792
	ds_read_b128 v[182:185], v193 offset:34816
	ds_read_b128 v[186:189], v193 offset:35840
	ds_read_b128 v[194:197], v193 offset:36864
	ds_read_b128 v[198:201], v193 offset:37888
	ds_read_b128 v[202:205], v193 offset:38912
	ds_read_b128 v[206:209], v193 offset:39936
	global_load_lds_dwordx4 v[190:191], off
	v_lshl_add_u64 v[190:191], v[210:211], 0, s[58:59]
	s_mov_b32 m0, s54
	s_nop 0
	global_load_lds_dwordx4 v[190:191], off
	s_waitcnt vmcnt(8)
	s_waitcnt lgkmcnt(0)
	s_barrier
	s_setprio 1
	s_waitcnt lgkmcnt(0)
	v_mfma_f32_16x16x32_bf16 v[126:129], v[130:133], v[174:177], v[126:129]
	v_mfma_f32_16x16x32_bf16 v[126:129], v[134:137], v[178:181], v[126:129]
	v_mfma_f32_16x16x32_bf16 v[122:125], v[138:141], v[174:177], v[122:125]
	v_mfma_f32_16x16x32_bf16 v[122:125], v[142:145], v[178:181], v[122:125]
	v_mfma_f32_16x16x32_bf16 v[118:121], v[130:133], v[182:185], v[118:121]
	v_mfma_f32_16x16x32_bf16 v[118:121], v[134:137], v[186:189], v[118:121]
	v_mfma_f32_16x16x32_bf16 v[114:117], v[138:141], v[182:185], v[114:117]
	v_mfma_f32_16x16x32_bf16 v[114:117], v[142:145], v[186:189], v[114:117]
	v_mfma_f32_16x16x32_bf16 v[110:113], v[130:133], v[194:197], v[110:113]
	v_mfma_f32_16x16x32_bf16 v[110:113], v[134:137], v[198:201], v[110:113]
	v_mfma_f32_16x16x32_bf16 v[106:109], v[138:141], v[194:197], v[106:109]
	v_mfma_f32_16x16x32_bf16 v[106:109], v[142:145], v[198:201], v[106:109]
	v_mfma_f32_16x16x32_bf16 v[102:105], v[130:133], v[202:205], v[102:105]
	v_mfma_f32_16x16x32_bf16 v[102:105], v[134:137], v[206:209], v[102:105]
	v_mfma_f32_16x16x32_bf16 v[98:101], v[138:141], v[202:205], v[98:101]
	v_mfma_f32_16x16x32_bf16 v[98:101], v[142:145], v[206:209], v[98:101]
	s_setprio 0
	s_setprio 1
	v_mfma_f32_16x16x32_bf16 v[30:33], v[146:149], v[174:177], v[30:33]
	v_mfma_f32_16x16x32_bf16 v[30:33], v[150:153], v[178:181], v[30:33]
	v_mfma_f32_16x16x32_bf16 v[46:49], v[154:157], v[174:177], v[46:49]
	v_mfma_f32_16x16x32_bf16 v[46:49], v[170:173], v[178:181], v[46:49]
	v_mfma_f32_16x16x32_bf16 v[26:29], v[146:149], v[182:185], v[26:29]
	v_mfma_f32_16x16x32_bf16 v[26:29], v[150:153], v[186:189], v[26:29]
	v_mfma_f32_16x16x32_bf16 v[34:37], v[154:157], v[182:185], v[34:37]
	v_mfma_f32_16x16x32_bf16 v[34:37], v[170:173], v[186:189], v[34:37]
	v_mfma_f32_16x16x32_bf16 v[94:97], v[146:149], v[194:197], v[94:97]
	v_mfma_f32_16x16x32_bf16 v[94:97], v[150:153], v[198:201], v[94:97]
	v_mfma_f32_16x16x32_bf16 v[90:93], v[154:157], v[194:197], v[90:93]
	v_mfma_f32_16x16x32_bf16 v[90:93], v[170:173], v[198:201], v[90:93]
	v_mfma_f32_16x16x32_bf16 v[86:89], v[146:149], v[202:205], v[86:89]
	v_mfma_f32_16x16x32_bf16 v[86:89], v[150:153], v[206:209], v[86:89]
	v_mfma_f32_16x16x32_bf16 v[82:85], v[154:157], v[202:205], v[82:85]
	v_mfma_f32_16x16x32_bf16 v[82:85], v[170:173], v[206:209], v[82:85]
	s_setprio 0
	s_barrier
; #define PG8_STAGE(bufoff, gbase, voff) do { _Pragma("unroll") for (int _i = 0; _i < 2; ++_i) \
;         __builtin_amdgcn_global_load_lds((const unsigned*)((const char*)(gbase) + (voff)[_i]), (PG8_LAS unsigned*)(lds + (bufoff) + ldsw + _i * 8192), 16, 0, 0); } while (0)
; #define PG8_LDA(dst, b, h) do { _Pragma("unroll") for (int m = 0; m < 4; ++m) _Pragma("unroll") for (int k = 0; k < 2; ++k) dst[m][k] = *(const PG8_LAS bf16x8*)(lds + PG8_SA(b, h) + aoff + m * 2048 + k * 1024); } while (0)
; #define PG8_MMA(ai, bj, At, Bt) do { __builtin_amdgcn_s_setprio(1); _Pragma("unroll") for (int m = 0; m < 4; ++m) _Pragma("unroll") for (int n = 0; n < 2; ++n) _Pragma("unroll") for (int k = 0; k < 2; ++k) \
;         acc[ai][bj][m][n] = __builtin_amdgcn_mfma_f32_16x16x32_bf16(Bt[n][k], At[m][k], acc[ai][bj][m][n], 0, 0, 0); __builtin_amdgcn_s_setprio(0); } while (0)
; #define PG8_WAIT_V(n) asm volatile("s_waitcnt vmcnt(" #n ")" ::: "memory")
; #define PG8_WAIT_L(n) asm volatile("s_waitcnt lgkmcnt(" #n ")" ::: "memory")
; #define PG8_BAR __builtin_amdgcn_s_barrier()
; #define PG8_SCHED __builtin_amdgcn_sched_barrier(0)
;     ...
;             PG8_WAIT_V(8); PG8_WAIT_L(0); PG8_BAR; PG8_MMA(0, 0, At, B0); PG8_MMA(0, 1, At, B1); PG8_BAR; PG8_SCHED;
;             PG8_LDA(At, 1, 1); PG8_STAGE(PG8_SB(1, 0), b3, voffB); PG8_STAGE(PG8_SB(1, 1), b3 + hstepB, voffB); PG8_STAGE(PG8_SA(1, 0), a3, voffA);
;             PG8_WAIT_V(8); PG8_WAIT_L(0); PG8_BAR; PG8_MMA(1, 0, At, B0); PG8_MMA(1, 1, At, B1); PG8_BAR; PG8_SCHED;
;     ...
;         if constexpr (ALIGN_EPI) { if (wr == 0) PG8_BAR; }
	s_add_u32 s34, s86, 0x8000
	s_addc_u32 s35, s87, 0
	s_add_i32 s88, s88, s44
	s_mov_b32 m0, s88
	ds_read_b128 v[174:177], v193 offset:49152
	ds_read_b128 v[178:181], v193 offset:50176
	ds_read_b128 v[182:185], v193 offset:51200
	ds_read_b128 v[186:189], v193 offset:52224
	ds_read_b128 v[194:197], v193 offset:53248
	ds_read_b128 v[198:201], v193 offset:54272
	ds_read_b128 v[202:205], v193 offset:55296
	ds_read_b128 v[206:209], v193 offset:56320
	global_load_lds_dwordx4 v162, s[34:35]
	s_add_i32 m0, s88, 0x2000
	v_lshl_add_u64 v[190:191], s[34:35], 0, v[158:159]
	s_add_u32 s34, s86, 0xc000
	s_addc_u32 s35, s87, 0
	s_add_i32 s86, s89, s44
	global_load_lds_dwordx4 v[190:191], off
	s_mov_b32 m0, s86
	s_nop 0
	global_load_lds_dwordx4 v162, s[34:35]
	s_add_i32 m0, s86, 0x2000
	s_nop 0
	global_load_lds_dwordx4 v158, s[34:35]
	s_mov_b32 m0, s85
	s_nop 0
	global_load_lds_dwordx4 v164, s[46:47]
	v_lshl_add_u64 v[190:191], s[46:47], 0, v[160:161]
	s_mov_b32 m0, s90
	s_nop 0
	global_load_lds_dwordx4 v[190:191], off
	s_waitcnt vmcnt(8)
	s_waitcnt lgkmcnt(0)
	s_barrier
	s_setprio 1
	s_waitcnt lgkmcnt(0)
	v_mfma_f32_16x16x32_bf16 v[78:81], v[130:133], v[174:177], v[78:81]
	v_mfma_f32_16x16x32_bf16 v[78:81], v[134:137], v[178:181], v[78:81]
	v_mfma_f32_16x16x32_bf16 v[74:77], v[138:141], v[174:177], v[74:77]
	v_mfma_f32_16x16x32_bf16 v[74:77], v[142:145], v[178:181], v[74:77]
	v_mfma_f32_16x16x32_bf16 v[70:73], v[130:133], v[182:185], v[70:73]
	v_mfma_f32_16x16x32_bf16 v[70:73], v[134:137], v[186:189], v[70:73]
	v_mfma_f32_16x16x32_bf16 v[66:69], v[138:141], v[182:185], v[66:69]
	v_mfma_f32_16x16x32_bf16 v[66:69], v[142:145], v[186:189], v[66:69]
	v_mfma_f32_16x16x32_bf16 v[42:45], v[130:133], v[194:197], v[42:45]
	v_mfma_f32_16x16x32_bf16 v[42:45], v[134:137], v[198:201], v[42:45]
	v_mfma_f32_16x16x32_bf16 v[6:9], v[138:141], v[194:197], v[6:9]
	v_mfma_f32_16x16x32_bf16 v[6:9], v[142:145], v[198:201], v[6:9]
	v_mfma_f32_16x16x32_bf16 v[38:41], v[130:133], v[202:205], v[38:41]
	v_mfma_f32_16x16x32_bf16 v[38:41], v[134:137], v[206:209], v[38:41]
	v_mfma_f32_16x16x32_bf16 v[2:5], v[138:141], v[202:205], v[2:5]
	v_mfma_f32_16x16x32_bf16 v[2:5], v[142:145], v[206:209], v[2:5]
	s_setprio 0
	s_setprio 1
	v_mfma_f32_16x16x32_bf16 v[62:65], v[146:149], v[174:177], v[62:65]
	v_mfma_f32_16x16x32_bf16 v[62:65], v[150:153], v[178:181], v[62:65]
	v_mfma_f32_16x16x32_bf16 v[58:61], v[154:157], v[174:177], v[58:61]
	v_mfma_f32_16x16x32_bf16 v[58:61], v[170:173], v[178:181], v[58:61]
	v_mfma_f32_16x16x32_bf16 v[54:57], v[146:149], v[182:185], v[54:57]
	v_mfma_f32_16x16x32_bf16 v[54:57], v[150:153], v[186:189], v[54:57]
	v_mfma_f32_16x16x32_bf16 v[50:53], v[154:157], v[182:185], v[50:53]
	v_mfma_f32_16x16x32_bf16 v[50:53], v[170:173], v[186:189], v[50:53]
	v_mfma_f32_16x16x32_bf16 v[22:25], v[146:149], v[194:197], v[22:25]
	v_mfma_f32_16x16x32_bf16 v[22:25], v[150:153], v[198:201], v[22:25]
	v_mfma_f32_16x16x32_bf16 v[18:21], v[154:157], v[194:197], v[18:21]
	v_mfma_f32_16x16x32_bf16 v[18:21], v[170:173], v[198:201], v[18:21]
	v_mfma_f32_16x16x32_bf16 v[14:17], v[146:149], v[202:205], v[14:17]
	v_mfma_f32_16x16x32_bf16 v[14:17], v[150:153], v[206:209], v[14:17]
	v_mfma_f32_16x16x32_bf16 v[10:13], v[154:157], v[202:205], v[10:13]
	v_mfma_f32_16x16x32_bf16 v[10:13], v[170:173], v[206:209], v[10:13]
	s_setprio 0
	s_barrier
	s_add_i32 s66, s66, 2
	s_add_u32 vcc_hi, vcc_hi, 0x10000
	s_addc_u32 s65, s65, 0
	s_cmp_gt_u32 s66, 29
	s_mov_b64 s[34:35], s[36:37]
	s_cbranch_scc0 .LBB0_1256
	s_and_b64 vcc, exec, s[18:19]
	s_cbranch_vccz .LBB0_1259
	s_barrier

; #define PG8_STAGE(bufoff, gbase, voff) do { _Pragma("unroll") for (int _i = 0; _i < 2; ++_i) \
;         __builtin_amdgcn_global_load_lds((const unsigned*)((const char*)(gbase) + (voff)[_i]), (PG8_LAS unsigned*)(lds + (bufoff) + ldsw + _i * 8192), 16, 0, 0); } while (0)
; #define PG8_LDA(dst, b, h) do { _Pragma("unroll") for (int m = 0; m < 4; ++m) _Pragma("unroll") for (int k = 0; k < 2; ++k) dst[m][k] = *(const PG8_LAS bf16x8*)(lds + PG8_SA(b, h) + aoff + m * 2048 + k * 1024); } while (0)
; #define PG8_LDB(dst, b, h) do { _Pragma("unroll") for (int n = 0; n < 2; ++n) _Pragma("unroll") for (int k = 0; k < 2; ++k) dst[n][k] = *(const PG8_LAS bf16x8*)(lds + PG8_SB(b, h) + boff + n * 2048 + k * 1024); } while (0)
; #define PG8_MMA(ai, bj, At, Bt) do { __builtin_amdgcn_s_setprio(1); _Pragma("unroll") for (int m = 0; m < 4; ++m) _Pragma("unroll") for (int n = 0; n < 2; ++n) _Pragma("unroll") for (int k = 0; k < 2; ++k) \
;         acc[ai][bj][m][n] = __builtin_amdgcn_mfma_f32_16x16x32_bf16(Bt[n][k], At[m][k], acc[ai][bj][m][n], 0, 0, 0); __builtin_amdgcn_s_setprio(0); } while (0)
; #define PG8_WAIT_V(n) asm volatile("s_waitcnt vmcnt(" #n ")" ::: "memory")
; #define PG8_WAIT_L(n) asm volatile("s_waitcnt lgkmcnt(" #n ")" ::: "memory")
; #define PG8_BAR __builtin_amdgcn_s_barrier()
; #define PG8_SCHED __builtin_amdgcn_sched_barrier(0)
;     ...
;             const bool last = (t == nt - 2);
;             const char* a1 = cA + (ptrdiff_t)(t + 1) * kstepA;
;             const char* a2 = last ? nA : cA + (ptrdiff_t)(t + 2) * kstepA; const char* b2 = last ? nB : cB + (ptrdiff_t)(t + 2) * kstep;
;             const char* a3 = a2 + kstepA; const char* b3 = b2 + kstep;
;             if (last && has_next) S.a_ready(nxt);
;             if constexpr (SP2) {
;             PG8_LDB(B0, 0, 0); PG8_LDB(B1, 0, 1); PG8_SCHED; PG8_LDA(At, 0, 0); PG8_STAGE(PG8_SA(1, 1), a1 + hstepA, voffA);
;             PG8_WAIT_V(8); PG8_WAIT_L(0); PG8_BAR; PG8_MMA(0, 0, At, B0); PG8_MMA(0, 1, At, B1); PG8_BAR; PG8_SCHED;
;             PG8_LDA(At, 0, 1); PG8_STAGE(PG8_SB(0, 0), b2, voffB); PG8_STAGE(PG8_SB(0, 1), b2 + hstepB, voffB); PG8_STAGE(PG8_SA(0, 0), a2, voffA);
;             PG8_WAIT_V(8); PG8_WAIT_L(0); PG8_BAR; PG8_MMA(1, 0, At, B0); PG8_MMA(1, 1, At, B1); PG8_BAR; PG8_SCHED;
.LBB0_1444:
	s_or_b32 s44, s56, 1
	s_lshl_b64 s[34:35], s[44:45], 15
	s_sub_u32 s34, 0, s34
	s_subb_u32 s35, 0, s35
	s_add_u32 s44, s28, s34
	s_addc_u32 s65, s29, s35
	s_add_u32 s34, s30, 0xffff8000
	s_addc_u32 s35, s31, -1
	s_add_i32 s66, 0, 0x10000
	v_add_u32_e32 v0, s66, v230
	s_add_i32 s90, 0, 0x14000
	s_waitcnt lgkmcnt(0)
	ds_read_b128 v[130:133], v0
	ds_read_b128 v[134:137], v0 offset:1024
	ds_read_b128 v[138:141], v0 offset:2048
	ds_read_b128 v[142:145], v0 offset:3072
	v_add_u32_e32 v0, s90, v230
	ds_read_b128 v[146:149], v0
	ds_read_b128 v[150:153], v0 offset:1024
	ds_read_b128 v[154:157], v0 offset:2048
	ds_read_b128 v[158:161], v0 offset:3072
	s_add_u32 s88, s44, 0x4000
	s_addc_u32 s89, s65, 0
	s_add_i32 m0, s46, 0xc000
	ds_read_b128 v[162:165], v231
	ds_read_b128 v[166:169], v231 offset:1024
	ds_read_b128 v[170:173], v231 offset:2048
	ds_read_b128 v[174:177], v231 offset:3072
	ds_read_b128 v[178:181], v231 offset:4096
	ds_read_b128 v[182:185], v231 offset:5120
	ds_read_b128 v[186:189], v231 offset:6144
	ds_read_b128 v[190:193], v231 offset:7168
	global_load_lds_dwordx4 v194, s[88:89]
	s_add_i32 m0, s46, 0xe000
	s_nop 0
	global_load_lds_dwordx4 v198, s[88:89]
	s_waitcnt vmcnt(8)
	s_waitcnt lgkmcnt(0)
	s_barrier
	s_setprio 1
	s_waitcnt lgkmcnt(0)
	v_mfma_f32_16x16x32_bf16 v[126:129], v[130:133], v[162:165], v[126:129]
	v_mfma_f32_16x16x32_bf16 v[126:129], v[134:137], v[166:169], v[126:129]
	v_mfma_f32_16x16x32_bf16 v[122:125], v[138:141], v[162:165], v[122:125]
	v_mfma_f32_16x16x32_bf16 v[122:125], v[142:145], v[166:169], v[122:125]
	v_mfma_f32_16x16x32_bf16 v[110:113], v[130:133], v[170:173], v[110:113]
	v_mfma_f32_16x16x32_bf16 v[110:113], v[134:137], v[174:177], v[110:113]
	v_mfma_f32_16x16x32_bf16 v[106:109], v[138:141], v[170:173], v[106:109]
	v_mfma_f32_16x16x32_bf16 v[106:109], v[142:145], v[174:177], v[106:109]
	v_mfma_f32_16x16x32_bf16 v[94:97], v[130:133], v[178:181], v[94:97]
	v_mfma_f32_16x16x32_bf16 v[94:97], v[134:137], v[182:185], v[94:97]
	v_mfma_f32_16x16x32_bf16 v[90:93], v[138:141], v[178:181], v[90:93]
	v_mfma_f32_16x16x32_bf16 v[90:93], v[142:145], v[182:185], v[90:93]
	v_mfma_f32_16x16x32_bf16 v[78:81], v[130:133], v[186:189], v[78:81]
	v_mfma_f32_16x16x32_bf16 v[78:81], v[134:137], v[190:193], v[78:81]
	v_mfma_f32_16x16x32_bf16 v[74:77], v[138:141], v[186:189], v[74:77]
	v_mfma_f32_16x16x32_bf16 v[74:77], v[142:145], v[190:193], v[74:77]
	s_setprio 0
	s_setprio 1
	v_mfma_f32_16x16x32_bf16 v[118:121], v[146:149], v[162:165], v[118:121]
	v_mfma_f32_16x16x32_bf16 v[118:121], v[150:153], v[166:169], v[118:121]
	v_mfma_f32_16x16x32_bf16 v[114:117], v[154:157], v[162:165], v[114:117]
	v_mfma_f32_16x16x32_bf16 v[114:117], v[158:161], v[166:169], v[114:117]
	v_mfma_f32_16x16x32_bf16 v[102:105], v[146:149], v[170:173], v[102:105]
	v_mfma_f32_16x16x32_bf16 v[102:105], v[150:153], v[174:177], v[102:105]
	v_mfma_f32_16x16x32_bf16 v[98:101], v[154:157], v[170:173], v[98:101]
	v_mfma_f32_16x16x32_bf16 v[98:101], v[158:161], v[174:177], v[98:101]
	v_mfma_f32_16x16x32_bf16 v[86:89], v[146:149], v[178:181], v[86:89]
	v_mfma_f32_16x16x32_bf16 v[86:89], v[150:153], v[182:185], v[86:89]
	v_mfma_f32_16x16x32_bf16 v[82:85], v[154:157], v[178:181], v[82:85]
	v_mfma_f32_16x16x32_bf16 v[82:85], v[158:161], v[182:185], v[82:85]
	v_mfma_f32_16x16x32_bf16 v[70:73], v[146:149], v[186:189], v[70:73]
	v_mfma_f32_16x16x32_bf16 v[70:73], v[150:153], v[190:193], v[70:73]
	v_mfma_f32_16x16x32_bf16 v[66:69], v[154:157], v[186:189], v[66:69]
	v_mfma_f32_16x16x32_bf16 v[66:69], v[158:161], v[190:193], v[66:69]
	s_setprio 0
	s_barrier
	s_add_i32 s44, s66, s41
	s_mov_b32 m0, s44
	ds_read_b128 v[162:165], v231 offset:16384
	ds_read_b128 v[166:169], v231 offset:17408
	ds_read_b128 v[170:173], v231 offset:18432
	ds_read_b128 v[174:177], v231 offset:19456
	ds_read_b128 v[178:181], v231 offset:20480
	ds_read_b128 v[182:185], v231 offset:21504
	ds_read_b128 v[186:189], v231 offset:22528
	ds_read_b128 v[190:193], v231 offset:23552
	global_load_lds_dwordx4 v196, s[8:9]
	s_add_i32 m0, s44, 0x2000
	s_add_u32 s88, s8, 0x4000
	s_addc_u32 s89, s9, 0
	s_add_i32 s44, s90, s41
	global_load_lds_dwordx4 v200, s[8:9]
	s_mov_b32 m0, s44
	s_nop 0
	global_load_lds_dwordx4 v196, s[88:89]
	s_add_i32 m0, s44, 0x2000
	s_nop 0
	global_load_lds_dwordx4 v200, s[88:89]
	s_mov_b32 m0, s46
	s_nop 0
	global_load_lds_dwordx4 v194, s[30:31]
	s_mov_b32 m0, s47
	s_nop 0
	global_load_lds_dwordx4 v198, s[30:31]
	s_waitcnt vmcnt(8)
	s_waitcnt lgkmcnt(0)
	s_barrier
; #define PG8_STAGE(bufoff, gbase, voff) do { _Pragma("unroll") for (int _i = 0; _i < 2; ++_i) \
;         __builtin_amdgcn_global_load_lds((const unsigned*)((const char*)(gbase) + (voff)[_i]), (PG8_LAS unsigned*)(lds + (bufoff) + ldsw + _i * 8192), 16, 0, 0); } while (0)
; #define PG8_LDA(dst, b, h) do { _Pragma("unroll") for (int m = 0; m < 4; ++m) _Pragma("unroll") for (int k = 0; k < 2; ++k) dst[m][k] = *(const PG8_LAS bf16x8*)(lds + PG8_SA(b, h) + aoff + m * 2048 + k * 1024); } while (0)
; #define PG8_LDB(dst, b, h) do { _Pragma("unroll") for (int n = 0; n < 2; ++n) _Pragma("unroll") for (int k = 0; k < 2; ++k) dst[n][k] = *(const PG8_LAS bf16x8*)(lds + PG8_SB(b, h) + boff + n * 2048 + k * 1024); } while (0)
; #define PG8_MMA(ai, bj, At, Bt) do { __builtin_amdgcn_s_setprio(1); _Pragma("unroll") for (int m = 0; m < 4; ++m) _Pragma("unroll") for (int n = 0; n < 2; ++n) _Pragma("unroll") for (int k = 0; k < 2; ++k) \
;         acc[ai][bj][m][n] = __builtin_amdgcn_mfma_f32_16x16x32_bf16(Bt[n][k], At[m][k], acc[ai][bj][m][n], 0, 0, 0); __builtin_amdgcn_s_setprio(0); } while (0)
; #define PG8_WAIT_V(n) asm volatile("s_waitcnt vmcnt(" #n ")" ::: "memory")
; #define PG8_WAIT_L(n) asm volatile("s_waitcnt lgkmcnt(" #n ")" ::: "memory")
; #define PG8_BAR __builtin_amdgcn_s_barrier()
; #define PG8_SCHED __builtin_amdgcn_sched_barrier(0)
;     ...
;             PG8_WAIT_V(8); PG8_WAIT_L(0); PG8_BAR; PG8_MMA(1, 0, At, B0); PG8_MMA(1, 1, At, B1); PG8_BAR; PG8_SCHED;
;             PG8_LDB(B0, 1, 0); PG8_LDB(B1, 1, 1); PG8_SCHED; PG8_LDA(At, 1, 0); PG8_STAGE(PG8_SA(0, 1), a2 + hstepA, voffA);
;             PG8_WAIT_V(8); PG8_WAIT_L(0); PG8_BAR; PG8_MMA(0, 0, At, B0); PG8_MMA(0, 1, At, B1); PG8_BAR; PG8_SCHED;
	s_setprio 1
	s_waitcnt lgkmcnt(0)
	v_mfma_f32_16x16x32_bf16 v[62:65], v[130:133], v[162:165], v[62:65]
	v_mfma_f32_16x16x32_bf16 v[62:65], v[134:137], v[166:169], v[62:65]
	v_mfma_f32_16x16x32_bf16 v[58:61], v[138:141], v[162:165], v[58:61]
	v_mfma_f32_16x16x32_bf16 v[58:61], v[142:145], v[166:169], v[58:61]
	v_mfma_f32_16x16x32_bf16 v[46:49], v[130:133], v[170:173], v[46:49]
	v_mfma_f32_16x16x32_bf16 v[46:49], v[134:137], v[174:177], v[46:49]
	v_mfma_f32_16x16x32_bf16 v[42:45], v[138:141], v[170:173], v[42:45]
	v_mfma_f32_16x16x32_bf16 v[42:45], v[142:145], v[174:177], v[42:45]
	v_mfma_f32_16x16x32_bf16 v[30:33], v[130:133], v[178:181], v[30:33]
	v_mfma_f32_16x16x32_bf16 v[30:33], v[134:137], v[182:185], v[30:33]
	v_mfma_f32_16x16x32_bf16 v[26:29], v[138:141], v[178:181], v[26:29]
	v_mfma_f32_16x16x32_bf16 v[26:29], v[142:145], v[182:185], v[26:29]
	v_mfma_f32_16x16x32_bf16 v[14:17], v[130:133], v[186:189], v[14:17]
	v_mfma_f32_16x16x32_bf16 v[14:17], v[134:137], v[190:193], v[14:17]
	v_mfma_f32_16x16x32_bf16 v[10:13], v[138:141], v[186:189], v[10:13]
	v_mfma_f32_16x16x32_bf16 v[10:13], v[142:145], v[190:193], v[10:13]
	s_setprio 0
	s_setprio 1
	v_mfma_f32_16x16x32_bf16 v[54:57], v[146:149], v[162:165], v[54:57]
	v_mfma_f32_16x16x32_bf16 v[54:57], v[150:153], v[166:169], v[54:57]
	v_mfma_f32_16x16x32_bf16 v[50:53], v[154:157], v[162:165], v[50:53]
	v_mfma_f32_16x16x32_bf16 v[50:53], v[158:161], v[166:169], v[50:53]
	v_mfma_f32_16x16x32_bf16 v[38:41], v[146:149], v[170:173], v[38:41]
	v_mfma_f32_16x16x32_bf16 v[38:41], v[150:153], v[174:177], v[38:41]
	v_mfma_f32_16x16x32_bf16 v[34:37], v[154:157], v[170:173], v[34:37]
	v_mfma_f32_16x16x32_bf16 v[34:37], v[158:161], v[174:177], v[34:37]
	v_mfma_f32_16x16x32_bf16 v[22:25], v[146:149], v[178:181], v[22:25]
	v_mfma_f32_16x16x32_bf16 v[22:25], v[150:153], v[182:185], v[22:25]
	v_mfma_f32_16x16x32_bf16 v[18:21], v[154:157], v[178:181], v[18:21]
	v_mfma_f32_16x16x32_bf16 v[18:21], v[158:161], v[182:185], v[18:21]
	v_mfma_f32_16x16x32_bf16 v[6:9], v[146:149], v[186:189], v[6:9]
	v_mfma_f32_16x16x32_bf16 v[6:9], v[150:153], v[190:193], v[6:9]
	v_mfma_f32_16x16x32_bf16 v[2:5], v[154:157], v[186:189], v[2:5]
	v_mfma_f32_16x16x32_bf16 v[2:5], v[158:161], v[190:193], v[2:5]
	s_setprio 0
	s_barrier
	s_add_i32 s44, 0, 0x18000
	v_add_u32_e32 v0, s44, v230
	s_add_i32 s65, 0, 0x1c000
	ds_read_b128 v[130:133], v0
	ds_read_b128 v[134:137], v0 offset:1024
	ds_read_b128 v[138:141], v0 offset:2048
	ds_read_b128 v[142:145], v0 offset:3072
	v_add_u32_e32 v0, s65, v230
	ds_read_b128 v[146:149], v0
	ds_read_b128 v[150:153], v0 offset:1024
	ds_read_b128 v[154:157], v0 offset:2048
	ds_read_b128 v[158:161], v0 offset:3072
	s_add_u32 s30, s30, 0x4000
	s_addc_u32 s31, s31, 0
	s_mov_b32 m0, s48
	ds_read_b128 v[162:165], v231 offset:32768
	ds_read_b128 v[166:169], v231 offset:33792
	ds_read_b128 v[170:173], v231 offset:34816
	ds_read_b128 v[174:177], v231 offset:35840
	ds_read_b128 v[178:181], v231 offset:36864
	ds_read_b128 v[182:185], v231 offset:37888
	ds_read_b128 v[186:189], v231 offset:38912
	ds_read_b128 v[190:193], v231 offset:39936
	global_load_lds_dwordx4 v194, s[30:31]
	s_mov_b32 m0, s49
	s_nop 0
	global_load_lds_dwordx4 v198, s[30:31]
	s_waitcnt vmcnt(8)
	s_waitcnt lgkmcnt(0)
	s_barrier
	s_setprio 1
	s_waitcnt lgkmcnt(0)
	v_mfma_f32_16x16x32_bf16 v[126:129], v[130:133], v[162:165], v[126:129]
	v_mfma_f32_16x16x32_bf16 v[126:129], v[134:137], v[166:169], v[126:129]
	v_mfma_f32_16x16x32_bf16 v[122:125], v[138:141], v[162:165], v[122:125]
	v_mfma_f32_16x16x32_bf16 v[122:125], v[142:145], v[166:169], v[122:125]
	v_mfma_f32_16x16x32_bf16 v[110:113], v[130:133], v[170:173], v[110:113]
	v_mfma_f32_16x16x32_bf16 v[110:113], v[134:137], v[174:177], v[110:113]
	v_mfma_f32_16x16x32_bf16 v[106:109], v[138:141], v[170:173], v[106:109]
	v_mfma_f32_16x16x32_bf16 v[106:109], v[142:145], v[174:177], v[106:109]
	v_mfma_f32_16x16x32_bf16 v[94:97], v[130:133], v[178:181], v[94:97]
	v_mfma_f32_16x16x32_bf16 v[94:97], v[134:137], v[182:185], v[94:97]
	v_mfma_f32_16x16x32_bf16 v[90:93], v[138:141], v[178:181], v[90:93]
	v_mfma_f32_16x16x32_bf16 v[90:93], v[142:145], v[182:185], v[90:93]
	v_mfma_f32_16x16x32_bf16 v[78:81], v[130:133], v[186:189], v[78:81]
	v_mfma_f32_16x16x32_bf16 v[78:81], v[134:137], v[190:193], v[78:81]
	v_mfma_f32_16x16x32_bf16 v[74:77], v[138:141], v[186:189], v[74:77]
	v_mfma_f32_16x16x32_bf16 v[74:77], v[142:145], v[190:193], v[74:77]
	s_setprio 0
	s_setprio 1
	v_mfma_f32_16x16x32_bf16 v[118:121], v[146:149], v[162:165], v[118:121]
	v_mfma_f32_16x16x32_bf16 v[118:121], v[150:153], v[166:169], v[118:121]
	v_mfma_f32_16x16x32_bf16 v[114:117], v[154:157], v[162:165], v[114:117]
	v_mfma_f32_16x16x32_bf16 v[114:117], v[158:161], v[166:169], v[114:117]
	v_mfma_f32_16x16x32_bf16 v[102:105], v[146:149], v[170:173], v[102:105]
	v_mfma_f32_16x16x32_bf16 v[102:105], v[150:153], v[174:177], v[102:105]
	v_mfma_f32_16x16x32_bf16 v[98:101], v[154:157], v[170:173], v[98:101]
	v_mfma_f32_16x16x32_bf16 v[98:101], v[158:161], v[174:177], v[98:101]
	v_mfma_f32_16x16x32_bf16 v[86:89], v[146:149], v[178:181], v[86:89]
	v_mfma_f32_16x16x32_bf16 v[86:89], v[150:153], v[182:185], v[86:89]
	v_mfma_f32_16x16x32_bf16 v[82:85], v[154:157], v[178:181], v[82:85]
	v_mfma_f32_16x16x32_bf16 v[82:85], v[158:161], v[182:185], v[82:85]
	v_mfma_f32_16x16x32_bf16 v[70:73], v[146:149], v[186:189], v[70:73]
	v_mfma_f32_16x16x32_bf16 v[70:73], v[150:153], v[190:193], v[70:73]
	v_mfma_f32_16x16x32_bf16 v[66:69], v[154:157], v[186:189], v[66:69]
	v_mfma_f32_16x16x32_bf16 v[66:69], v[158:161], v[190:193], v[66:69]
	s_setprio 0
	s_barrier
; #define PG8_STAGE(bufoff, gbase, voff) do { _Pragma("unroll") for (int _i = 0; _i < 2; ++_i) \
;         __builtin_amdgcn_global_load_lds((const unsigned*)((const char*)(gbase) + (voff)[_i]), (PG8_LAS unsigned*)(lds + (bufoff) + ldsw + _i * 8192), 16, 0, 0); } while (0)
; #define PG8_LDA(dst, b, h) do { _Pragma("unroll") for (int m = 0; m < 4; ++m) _Pragma("unroll") for (int k = 0; k < 2; ++k) dst[m][k] = *(const PG8_LAS bf16x8*)(lds + PG8_SA(b, h) + aoff + m * 2048 + k * 1024); } while (0)
; #define PG8_MMA(ai, bj, At, Bt) do { __builtin_amdgcn_s_setprio(1); _Pragma("unroll") for (int m = 0; m < 4; ++m) _Pragma("unroll") for (int n = 0; n < 2; ++n) _Pragma("unroll") for (int k = 0; k < 2; ++k) \
;         acc[ai][bj][m][n] = __builtin_amdgcn_mfma_f32_16x16x32_bf16(Bt[n][k], At[m][k], acc[ai][bj][m][n], 0, 0, 0); __builtin_amdgcn_s_setprio(0); } while (0)
; #define PG8_WAIT_V(n) asm volatile("s_waitcnt vmcnt(" #n ")" ::: "memory")
; #define PG8_WAIT_L(n) asm volatile("s_waitcnt lgkmcnt(" #n ")" ::: "memory")
; #define PG8_BAR __builtin_amdgcn_s_barrier()
; #define PG8_SCHED __builtin_amdgcn_sched_barrier(0)
;     ...
;             PG8_LDA(At, 1, 1); PG8_STAGE(PG8_SB(1, 0), b3, voffB); PG8_STAGE(PG8_SB(1, 1), b3 + hstepB, voffB); PG8_STAGE(PG8_SA(1, 0), a3, voffA);
;             PG8_WAIT_V(8); PG8_WAIT_L(0); PG8_BAR; PG8_MMA(1, 0, At, B0); PG8_MMA(1, 1, At, B1); PG8_BAR; PG8_SCHED;
	s_add_u32 s30, s8, 0xffff8000
	s_addc_u32 s31, s9, -1
	s_add_i32 s44, s44, s41
	s_mov_b32 m0, s44
	ds_read_b128 v[162:165], v231 offset:49152
	ds_read_b128 v[166:169], v231 offset:50176
	ds_read_b128 v[170:173], v231 offset:51200
	ds_read_b128 v[174:177], v231 offset:52224
	ds_read_b128 v[178:181], v231 offset:53248
	ds_read_b128 v[182:185], v231 offset:54272
	ds_read_b128 v[186:189], v231 offset:55296
	ds_read_b128 v[190:193], v231 offset:56320
	global_load_lds_dwordx4 v196, s[30:31]
	s_add_i32 m0, s44, 0x2000
	s_add_u32 s8, s8, 0xffffc000
	v_lshl_add_u64 v[202:203], s[30:31], 0, v[200:201]
	s_addc_u32 s9, s9, -1
	s_add_i32 s30, s65, s41
	global_load_lds_dwordx4 v[202:203], off
	s_mov_b32 m0, s30
	s_nop 0
	global_load_lds_dwordx4 v196, s[8:9]
	s_add_i32 m0, s30, 0x2000
	s_nop 0
	global_load_lds_dwordx4 v200, s[8:9]
	s_mov_b32 m0, s71
	s_nop 0
	global_load_lds_dwordx4 v194, s[34:35]
	v_lshl_add_u64 v[202:203], s[34:35], 0, v[198:199]
	s_mov_b32 m0, s80
	s_nop 0
	global_load_lds_dwordx4 v[202:203], off
	s_waitcnt vmcnt(8)
	s_waitcnt lgkmcnt(0)
	s_barrier
	s_setprio 1
	s_waitcnt lgkmcnt(0)
	v_mfma_f32_16x16x32_bf16 v[62:65], v[130:133], v[162:165], v[62:65]
	v_mfma_f32_16x16x32_bf16 v[62:65], v[134:137], v[166:169], v[62:65]
	v_mfma_f32_16x16x32_bf16 v[58:61], v[138:141], v[162:165], v[58:61]
	v_mfma_f32_16x16x32_bf16 v[58:61], v[142:145], v[166:169], v[58:61]
	v_mfma_f32_16x16x32_bf16 v[46:49], v[130:133], v[170:173], v[46:49]
	v_mfma_f32_16x16x32_bf16 v[46:49], v[134:137], v[174:177], v[46:49]
	v_mfma_f32_16x16x32_bf16 v[42:45], v[138:141], v[170:173], v[42:45]
	v_mfma_f32_16x16x32_bf16 v[42:45], v[142:145], v[174:177], v[42:45]
	v_mfma_f32_16x16x32_bf16 v[30:33], v[130:133], v[178:181], v[30:33]
	v_mfma_f32_16x16x32_bf16 v[30:33], v[134:137], v[182:185], v[30:33]
	v_mfma_f32_16x16x32_bf16 v[26:29], v[138:141], v[178:181], v[26:29]
	v_mfma_f32_16x16x32_bf16 v[26:29], v[142:145], v[182:185], v[26:29]
	v_mfma_f32_16x16x32_bf16 v[14:17], v[130:133], v[186:189], v[14:17]
	v_mfma_f32_16x16x32_bf16 v[14:17], v[134:137], v[190:193], v[14:17]
	v_mfma_f32_16x16x32_bf16 v[10:13], v[138:141], v[186:189], v[10:13]
	v_mfma_f32_16x16x32_bf16 v[10:13], v[142:145], v[190:193], v[10:13]
	s_setprio 0
	s_setprio 1
	v_mfma_f32_16x16x32_bf16 v[54:57], v[146:149], v[162:165], v[54:57]
	v_mfma_f32_16x16x32_bf16 v[54:57], v[150:153], v[166:169], v[54:57]
	v_mfma_f32_16x16x32_bf16 v[50:53], v[154:157], v[162:165], v[50:53]
	v_mfma_f32_16x16x32_bf16 v[50:53], v[158:161], v[166:169], v[50:53]
	v_mfma_f32_16x16x32_bf16 v[38:41], v[146:149], v[170:173], v[38:41]
	v_mfma_f32_16x16x32_bf16 v[38:41], v[150:153], v[174:177], v[38:41]
	v_mfma_f32_16x16x32_bf16 v[34:37], v[154:157], v[170:173], v[34:37]
	v_mfma_f32_16x16x32_bf16 v[34:37], v[158:161], v[174:177], v[34:37]
	v_mfma_f32_16x16x32_bf16 v[22:25], v[146:149], v[178:181], v[22:25]
	v_mfma_f32_16x16x32_bf16 v[22:25], v[150:153], v[182:185], v[22:25]
	v_mfma_f32_16x16x32_bf16 v[18:21], v[154:157], v[178:181], v[18:21]
	v_mfma_f32_16x16x32_bf16 v[18:21], v[158:161], v[182:185], v[18:21]
	v_mfma_f32_16x16x32_bf16 v[6:9], v[146:149], v[186:189], v[6:9]
	v_mfma_f32_16x16x32_bf16 v[6:9], v[150:153], v[190:193], v[6:9]
	v_mfma_f32_16x16x32_bf16 v[2:5], v[154:157], v[186:189], v[2:5]
	v_mfma_f32_16x16x32_bf16 v[2:5], v[158:161], v[190:193], v[2:5]
	s_setprio 0
	s_barrier
	s_cmpk_gt_u32 s56, 0x55
	s_mov_b32 s56, s57
	s_cbranch_scc1 .LBB0_1449
